# residual-add GEMM epilogue rewritten: 16 residual loads in flight, second half's loads overlap first half's adds and stores
# speedup vs baseline: 1.0116x; 1.0006x over previous
; template <class F>
; DI void gemm_phase(const int tid, LAS unsigned char* lds, const bf16_t* Ap, int lda, const bf16_t* Bp, int ldb, int M, int N, int K, int G, int c, bool direct, const F& E) {
;     ...
;         else if (E.kind == 1  ) {
;             const int row0 = cur.pm * BM + wr * 64 + fr, col0 = cur.pn * BM + wc * 32 + 8 * fq;
; #pragma unroll
;             for (int ai = 0; ai < 2; ++ai) {
;                 f32x4 r[4][2][2];
; #pragma unroll
;                 for (int m = 0; m < 4; ++m)
; #pragma unroll
;                     for (int bj = 0; bj < 2; ++bj) { const size_t o = (size_t)(row0 + ai * HALF + m * 16) * 1024 + col0 + bj * HALF;
;                         r[m][bj][0] = *(const f32x4*)(E.cf0 + o); r[m][bj][1] = *(const f32x4*)(E.cf0 + o + 4); }
; #pragma unroll
;                 for (int m = 0; m < 4; ++m)
; #pragma unroll
;                     for (int bj = 0; bj < 2; ++bj) { const size_t o = (size_t)(row0 + ai * HALF + m * 16) * 1024 + col0 + bj * HALF;
;                         *(f32x4*)(E.f0 + o) = r[m][bj][0] + acc[ai][bj][m][0]; *(f32x4*)(E.f0 + o + 4) = r[m][bj][1] + acc[ai][bj][m][1]; }
;             }
.Lresid_epi:
	v_lshl_add_u32 v228, s36, 8, v183
	s_lshl_b32 s71, s70, 8
	v_or_b32_e32 v229, s71, v194
	v_lshlrev_b32_e32 v229, 2, v229
	v_lshl_add_u32 v228, v228, 12, v229
	global_load_dwordx4 v[128:131], v228, s[22:23]
	global_load_dwordx4 v[132:135], v228, s[22:23] offset:16
	global_load_dwordx4 v[136:139], v228, s[22:23] offset:512
	global_load_dwordx4 v[140:143], v228, s[22:23] offset:528
	s_add_u32 s76, s22, 0x10000
	s_addc_u32 s77, s23, 0
	global_load_dwordx4 v[144:147], v228, s[76:77]
	global_load_dwordx4 v[148:151], v228, s[76:77] offset:16
	global_load_dwordx4 v[152:155], v228, s[76:77] offset:512
	global_load_dwordx4 v[156:159], v228, s[76:77] offset:528
	s_add_u32 s76, s22, 0x20000
	s_addc_u32 s77, s23, 0
	global_load_dwordx4 v[160:163], v228, s[76:77]
	global_load_dwordx4 v[164:167], v228, s[76:77] offset:16
	global_load_dwordx4 v[168:171], v228, s[76:77] offset:512
	global_load_dwordx4 v[172:175], v228, s[76:77] offset:528
	s_add_u32 s76, s22, 0x30000
	s_addc_u32 s77, s23, 0
	global_load_dwordx4 v[208:211], v228, s[76:77]
	global_load_dwordx4 v[212:215], v228, s[76:77] offset:16
	global_load_dwordx4 v[216:219], v228, s[76:77] offset:512
	global_load_dwordx4 v[220:223], v228, s[76:77] offset:528
	s_waitcnt vmcnt(12)
	v_pk_add_f32 v[124:125], v[124:125], v[128:129]
	v_pk_add_f32 v[126:127], v[126:127], v[130:131]
	v_pk_add_f32 v[120:121], v[120:121], v[132:133]
	v_pk_add_f32 v[122:123], v[122:123], v[134:135]
	v_pk_add_f32 v[112:113], v[112:113], v[136:137]
	v_pk_add_f32 v[114:115], v[114:115], v[138:139]
	v_pk_add_f32 v[108:109], v[108:109], v[140:141]
	v_pk_add_f32 v[110:111], v[110:111], v[142:143]
	global_store_dwordx4 v228, v[124:127], s[8:9]
	global_store_dwordx4 v228, v[120:123], s[8:9] offset:16
	global_store_dwordx4 v228, v[112:115], s[8:9] offset:512
	global_store_dwordx4 v228, v[108:111], s[8:9] offset:528
	s_add_u32 s76, s22, 0x80000
	s_addc_u32 s77, s23, 0
	global_load_dwordx4 v[128:131], v228, s[76:77]
	global_load_dwordx4 v[132:135], v228, s[76:77] offset:16
	global_load_dwordx4 v[136:139], v228, s[76:77] offset:512
	global_load_dwordx4 v[140:143], v228, s[76:77] offset:528
	s_waitcnt vmcnt(16)
	v_pk_add_f32 v[116:117], v[116:117], v[144:145]
	v_pk_add_f32 v[118:119], v[118:119], v[146:147]
	v_pk_add_f32 v[104:105], v[104:105], v[148:149]
	v_pk_add_f32 v[106:107], v[106:107], v[150:151]
	v_pk_add_f32 v[96:97], v[96:97], v[152:153]
	v_pk_add_f32 v[98:99], v[98:99], v[154:155]
	v_pk_add_f32 v[92:93], v[92:93], v[156:157]
	v_pk_add_f32 v[94:95], v[94:95], v[158:159]
	s_add_u32 s80, s8, 0x10000
	s_addc_u32 s81, s9, 0
	global_store_dwordx4 v228, v[116:119], s[80:81]
	global_store_dwordx4 v228, v[104:107], s[80:81] offset:16
	global_store_dwordx4 v228, v[96:99], s[80:81] offset:512
	global_store_dwordx4 v228, v[92:95], s[80:81] offset:528
	s_add_u32 s76, s22, 0x90000
	s_addc_u32 s77, s23, 0
	global_load_dwordx4 v[144:147], v228, s[76:77]
	global_load_dwordx4 v[148:151], v228, s[76:77] offset:16
	global_load_dwordx4 v[152:155], v228, s[76:77] offset:512
	global_load_dwordx4 v[156:159], v228, s[76:77] offset:528
	s_waitcnt vmcnt(20)
	v_pk_add_f32 v[100:101], v[100:101], v[160:161]
	v_pk_add_f32 v[102:103], v[102:103], v[162:163]
	v_pk_add_f32 v[88:89], v[88:89], v[164:165]
	v_pk_add_f32 v[90:91], v[90:91], v[166:167]
	v_pk_add_f32 v[80:81], v[80:81], v[168:169]
	v_pk_add_f32 v[82:83], v[82:83], v[170:171]
	v_pk_add_f32 v[76:77], v[76:77], v[172:173]
	v_pk_add_f32 v[78:79], v[78:79], v[174:175]
	s_add_u32 s80, s8, 0x20000
	s_addc_u32 s81, s9, 0
	global_store_dwordx4 v228, v[100:103], s[80:81]
	global_store_dwordx4 v228, v[88:91], s[80:81] offset:16
	global_store_dwordx4 v228, v[80:83], s[80:81] offset:512
	global_store_dwordx4 v228, v[76:79], s[80:81] offset:528
	s_add_u32 s76, s22, 0xa0000
	s_addc_u32 s77, s23, 0
	global_load_dwordx4 v[160:163], v228, s[76:77]
	global_load_dwordx4 v[164:167], v228, s[76:77] offset:16
	global_load_dwordx4 v[168:171], v228, s[76:77] offset:512
	global_load_dwordx4 v[172:175], v228, s[76:77] offset:528
	s_waitcnt vmcnt(24)
; template <class F>
; DI void gemm_phase(const int tid, LAS unsigned char* lds, const bf16_t* Ap, int lda, const bf16_t* Bp, int ldb, int M, int N, int K, int G, int c, bool direct, const F& E) {
;     ...
;         else if (E.kind == 1  ) {
;             const int row0 = cur.pm * BM + wr * 64 + fr, col0 = cur.pn * BM + wc * 32 + 8 * fq;
; #pragma unroll
;             for (int ai = 0; ai < 2; ++ai) {
;                 f32x4 r[4][2][2];
; #pragma unroll
;                 for (int m = 0; m < 4; ++m)
; #pragma unroll
;                     for (int bj = 0; bj < 2; ++bj) { const size_t o = (size_t)(row0 + ai * HALF + m * 16) * 1024 + col0 + bj * HALF;
;                         r[m][bj][0] = *(const f32x4*)(E.cf0 + o); r[m][bj][1] = *(const f32x4*)(E.cf0 + o + 4); }
; #pragma unroll
;                 for (int m = 0; m < 4; ++m)
; #pragma unroll
;                     for (int bj = 0; bj < 2; ++bj) { const size_t o = (size_t)(row0 + ai * HALF + m * 16) * 1024 + col0 + bj * HALF;
;                         *(f32x4*)(E.f0 + o) = r[m][bj][0] + acc[ai][bj][m][0]; *(f32x4*)(E.f0 + o + 4) = r[m][bj][1] + acc[ai][bj][m][1]; }
;             }
	v_pk_add_f32 v[84:85], v[84:85], v[208:209]
	v_pk_add_f32 v[86:87], v[86:87], v[210:211]
	v_pk_add_f32 v[72:73], v[72:73], v[212:213]
	v_pk_add_f32 v[74:75], v[74:75], v[214:215]
	v_pk_add_f32 v[68:69], v[68:69], v[216:217]
	v_pk_add_f32 v[70:71], v[70:71], v[218:219]
	v_pk_add_f32 v[64:65], v[64:65], v[220:221]
	v_pk_add_f32 v[66:67], v[66:67], v[222:223]
	s_add_u32 s80, s8, 0x30000
	s_addc_u32 s81, s9, 0
	global_store_dwordx4 v228, v[84:87], s[80:81]
	global_store_dwordx4 v228, v[72:75], s[80:81] offset:16
	global_store_dwordx4 v228, v[68:71], s[80:81] offset:512
	global_store_dwordx4 v228, v[64:67], s[80:81] offset:528
	s_add_u32 s76, s22, 0xb0000
	s_addc_u32 s77, s23, 0
	global_load_dwordx4 v[208:211], v228, s[76:77]
	global_load_dwordx4 v[212:215], v228, s[76:77] offset:16
	global_load_dwordx4 v[216:219], v228, s[76:77] offset:512
	global_load_dwordx4 v[220:223], v228, s[76:77] offset:528
	s_waitcnt vmcnt(24)
	v_pk_add_f32 v[60:61], v[60:61], v[128:129]
	v_pk_add_f32 v[62:63], v[62:63], v[130:131]
	v_pk_add_f32 v[56:57], v[56:57], v[132:133]
	v_pk_add_f32 v[58:59], v[58:59], v[134:135]
	v_pk_add_f32 v[48:49], v[48:49], v[136:137]
	v_pk_add_f32 v[50:51], v[50:51], v[138:139]
	v_pk_add_f32 v[44:45], v[44:45], v[140:141]
	v_pk_add_f32 v[46:47], v[46:47], v[142:143]
	s_add_u32 s80, s8, 0x80000
	s_addc_u32 s81, s9, 0
	global_store_dwordx4 v228, v[60:63], s[80:81]
	global_store_dwordx4 v228, v[56:59], s[80:81] offset:16
	global_store_dwordx4 v228, v[48:51], s[80:81] offset:512
	global_store_dwordx4 v228, v[44:47], s[80:81] offset:528
	s_waitcnt vmcnt(20)
	v_pk_add_f32 v[52:53], v[52:53], v[144:145]
	v_pk_add_f32 v[54:55], v[54:55], v[146:147]
	v_pk_add_f32 v[40:41], v[40:41], v[148:149]
	v_pk_add_f32 v[42:43], v[42:43], v[150:151]
	v_pk_add_f32 v[24:25], v[24:25], v[152:153]
	v_pk_add_f32 v[26:27], v[26:27], v[154:155]
	v_pk_add_f32 v[20:21], v[20:21], v[156:157]
	v_pk_add_f32 v[22:23], v[22:23], v[158:159]
	s_add_u32 s80, s8, 0x90000
	s_addc_u32 s81, s9, 0
	global_store_dwordx4 v228, v[52:55], s[80:81]
	global_store_dwordx4 v228, v[40:43], s[80:81] offset:16
	global_store_dwordx4 v228, v[24:27], s[80:81] offset:512
	global_store_dwordx4 v228, v[20:23], s[80:81] offset:528
	s_waitcnt vmcnt(16)
	v_pk_add_f32 v[36:37], v[36:37], v[160:161]
	v_pk_add_f32 v[38:39], v[38:39], v[162:163]
	v_pk_add_f32 v[16:17], v[16:17], v[164:165]
	v_pk_add_f32 v[18:19], v[18:19], v[166:167]
	v_pk_add_f32 v[28:29], v[28:29], v[168:169]
	v_pk_add_f32 v[30:31], v[30:31], v[170:171]
	v_pk_add_f32 v[32:33], v[32:33], v[172:173]
	v_pk_add_f32 v[34:35], v[34:35], v[174:175]
	s_add_u32 s80, s8, 0xa0000
	s_addc_u32 s81, s9, 0
	global_store_dwordx4 v228, v[36:39], s[80:81]
	global_store_dwordx4 v228, v[16:19], s[80:81] offset:16
	global_store_dwordx4 v228, v[28:31], s[80:81] offset:512
	global_store_dwordx4 v228, v[32:35], s[80:81] offset:528
	s_waitcnt vmcnt(12)
	v_pk_add_f32 v[12:13], v[12:13], v[208:209]
	v_pk_add_f32 v[14:15], v[14:15], v[210:211]
	v_pk_add_f32 v[0:1], v[0:1], v[212:213]
	v_pk_add_f32 v[2:3], v[2:3], v[214:215]
	v_pk_add_f32 v[8:9], v[8:9], v[216:217]
	v_pk_add_f32 v[10:11], v[10:11], v[218:219]
	v_pk_add_f32 v[4:5], v[4:5], v[220:221]
	v_pk_add_f32 v[6:7], v[6:7], v[222:223]
	s_add_u32 s80, s8, 0xb0000
	s_addc_u32 s81, s9, 0
	global_store_dwordx4 v228, v[12:15], s[80:81]
	global_store_dwordx4 v228, v[0:3], s[80:81] offset:16
	global_store_dwordx4 v228, v[8:11], s[80:81] offset:512
	global_store_dwordx4 v228, v[4:7], s[80:81] offset:528

; #define PG8_STAGE(bufoff, gbase, voff) do { _Pragma("unroll") for (int _i = 0; _i < 2; ++_i) \
;         __builtin_amdgcn_global_load_lds((const unsigned*)((const char*)(gbase) + (voff)[_i]), (LAS unsigned*)(lds + (bufoff) + ldsw + _i * 8192), 16, 0, 0); } while (0)
; #define PG8_LDA(dst, b, h) do { _Pragma("unroll") for (int m = 0; m < 4; ++m) _Pragma("unroll") for (int k = 0; k < 2; ++k) dst[m][k] = *(const LAS bf16x8*)(lds + PG8_SA(b, h) + aoff + m * 2048 + k * 1024); } while (0)
; #define PG8_LDB(dst, b, h) do { _Pragma("unroll") for (int n = 0; n < 2; ++n) _Pragma("unroll") for (int k = 0; k < 2; ++k) dst[n][k] = *(const LAS bf16x8*)(lds + PG8_SB(b, h) + boff + n * 2048 + k * 1024); } while (0)
; #define PG8_MMA(ai, bj, At, Bt) do { __builtin_amdgcn_s_setprio(1); _Pragma("unroll") for (int m = 0; m < 4; ++m) _Pragma("unroll") for (int n = 0; n < 2; ++n) _Pragma("unroll") for (int k = 0; k < 2; ++k) \
;         acc[ai][bj][m][n] = __builtin_amdgcn_mfma_f32_16x16x32_bf16(Bt[n][k], At[m][k], acc[ai][bj][m][n], 0, 0, 0); __builtin_amdgcn_s_setprio(0); } while (0)
; #define PG8_WAIT_V(n) asm volatile("s_waitcnt vmcnt(" #n ")" ::: "memory")
; #define PG8_WAIT_L(n) asm volatile("s_waitcnt lgkmcnt(" #n ")" ::: "memory")
; #define PG8_BAR __builtin_amdgcn_s_barrier()
; #define PG8_SCHED __builtin_amdgcn_sched_barrier(0)
; template <class F>
; DI void gemm_phase(const int tid, LAS unsigned char* lds, const bf16_t* Ap, int lda, const bf16_t* Bp, int ldb, int M, int N, int K, int G, int c, bool direct, const F& E) {
;     ...
;             PG8_LDB(B0, 0, 0); PG8_SCHED; PG8_LDA(At, 0, 0); PG8_STAGE(PG8_SA(1, 1), a1 + hsA, voffA);
;             PG8_WAIT_L(8); PG8_BAR; PG8_WAIT_L(0); PG8_MMA(0, 0, At, B0); PG8_BAR; PG8_SCHED;
;             PG8_LDB(B1, 0, 1); PG8_STAGE(PG8_SB(0, 0), b2, voffB);
;             PG8_BAR; PG8_WAIT_L(0); PG8_MMA(0, 1, At, B1); PG8_BAR;
;             PG8_LDA(At, 0, 1); PG8_STAGE(PG8_SA(0, 0), a2, voffA);
;             PG8_BAR; PG8_WAIT_L(0); PG8_MMA(1, 0, At, B0); PG8_BAR; PG8_SCHED;
;             PG8_STAGE(PG8_SB(0, 1), b2 + hsB, voffB);
;             PG8_WAIT_V(6); PG8_BAR; PG8_MMA(1, 1, At, B1); PG8_BAR;
;             PG8_LDB(B0, 1, 0); PG8_SCHED; PG8_LDA(At, 1, 0); PG8_STAGE(PG8_SA(0, 1), a2 + hsA, voffA);
.LBB0_657:
	s_add_i32 s81, s76, 2
	s_add_u32 s78, s74, 0x80
	s_addc_u32 s77, s75, 0
	s_add_i32 s82, 0, 0x10000
	v_add_u32_e32 v140, s82, v189
	ds_read_b128 v[128:131], v140
	ds_read_b128 v[132:135], v140 offset:1024
	ds_read_b128 v[136:139], v140 offset:2048
	ds_read_b128 v[140:143], v140 offset:3072
	s_cmp_eq_u32 s67, s76
	s_cselect_b32 s76, s0, s78
	s_cselect_b32 s77, s1, s77
	s_cselect_b32 s79, s5, s80
	s_cselect_b32 s78, s4, s71
	s_add_u32 s98, s78, 0x80
	s_addc_u32 s99, s79, 0
	s_add_u32 s100, s76, 0x80
	s_addc_u32 s101, s77, 0
	s_add_i32 m0, s28, 0xc000
	ds_read_b128 v[144:147], v197
	ds_read_b128 v[148:151], v197 offset:1024
	ds_read_b128 v[152:155], v197 offset:2048
	ds_read_b128 v[156:159], v197 offset:3072
	ds_read_b128 v[160:163], v197 offset:4096
	ds_read_b128 v[164:167], v197 offset:5120
	ds_read_b128 v[168:171], v197 offset:6144
	ds_read_b128 v[172:175], v197 offset:7168
	global_load_lds_dwordx4 v204, s[74:75]
	s_add_i32 m0, s28, 0xe000
	s_nop 0
	global_load_lds_dwordx4 v206, s[74:75]
	s_waitcnt lgkmcnt(8)
	s_barrier
	s_waitcnt lgkmcnt(0)
	s_waitcnt lgkmcnt(0)
	v_mfma_f32_16x16x32_bf16 v[124:127], v[128:131], v[144:147], v[124:127]
	v_mfma_f32_16x16x32_bf16 v[120:123], v[136:139], v[144:147], v[120:123]
	v_mfma_f32_16x16x32_bf16 v[116:119], v[128:131], v[152:155], v[116:119]
	v_mfma_f32_16x16x32_bf16 v[104:107], v[136:139], v[152:155], v[104:107]
	v_mfma_f32_16x16x32_bf16 v[100:103], v[128:131], v[160:163], v[100:103]
	v_mfma_f32_16x16x32_bf16 v[88:91], v[136:139], v[160:163], v[88:91]
	v_mfma_f32_16x16x32_bf16 v[84:87], v[128:131], v[168:171], v[84:87]
	v_mfma_f32_16x16x32_bf16 v[72:75], v[136:139], v[168:171], v[72:75]
	v_mfma_f32_16x16x32_bf16 v[124:127], v[132:135], v[148:151], v[124:127]
	v_mfma_f32_16x16x32_bf16 v[120:123], v[140:143], v[148:151], v[120:123]
	v_mfma_f32_16x16x32_bf16 v[116:119], v[132:135], v[156:159], v[116:119]
	v_mfma_f32_16x16x32_bf16 v[104:107], v[140:143], v[156:159], v[104:107]
	v_mfma_f32_16x16x32_bf16 v[100:103], v[132:135], v[164:167], v[100:103]
	v_mfma_f32_16x16x32_bf16 v[88:91], v[140:143], v[164:167], v[88:91]
	v_mfma_f32_16x16x32_bf16 v[84:87], v[132:135], v[172:175], v[84:87]
	v_mfma_f32_16x16x32_bf16 v[72:75], v[140:143], v[172:175], v[72:75]
	s_barrier
	s_add_i32 s82, s82, s27
	v_add_u32_e32 v180, s95, v189
	s_mov_b32 m0, s82
	ds_read_b128 v[208:211], v180
	ds_read_b128 v[212:215], v180 offset:1024
	ds_read_b128 v[216:219], v180 offset:2048
	ds_read_b128 v[220:223], v180 offset:3072
	global_load_lds_dwordx4 v178, s[78:79]
	s_add_i32 m0, s82, 0x2000
	s_nop 0
	global_load_lds_dwordx4 v186, s[78:79]
	s_barrier
	s_waitcnt lgkmcnt(0)
	s_waitcnt lgkmcnt(0)
	v_mfma_f32_16x16x32_bf16 v[112:115], v[208:211], v[144:147], v[112:115]
	v_mfma_f32_16x16x32_bf16 v[108:111], v[216:219], v[144:147], v[108:111]
	v_mfma_f32_16x16x32_bf16 v[96:99], v[208:211], v[152:155], v[96:99]
	v_mfma_f32_16x16x32_bf16 v[92:95], v[216:219], v[152:155], v[92:95]
	v_mfma_f32_16x16x32_bf16 v[80:83], v[208:211], v[160:163], v[80:83]
	v_mfma_f32_16x16x32_bf16 v[76:79], v[216:219], v[160:163], v[76:79]
	v_mfma_f32_16x16x32_bf16 v[68:71], v[208:211], v[168:171], v[68:71]
	v_mfma_f32_16x16x32_bf16 v[64:67], v[216:219], v[168:171], v[64:67]
	v_mfma_f32_16x16x32_bf16 v[112:115], v[212:215], v[148:151], v[112:115]
	v_mfma_f32_16x16x32_bf16 v[108:111], v[220:223], v[148:151], v[108:111]
	v_mfma_f32_16x16x32_bf16 v[96:99], v[212:215], v[156:159], v[96:99]
	v_mfma_f32_16x16x32_bf16 v[92:95], v[220:223], v[156:159], v[92:95]
	v_mfma_f32_16x16x32_bf16 v[80:83], v[212:215], v[164:167], v[80:83]
	v_mfma_f32_16x16x32_bf16 v[76:79], v[220:223], v[164:167], v[76:79]
	v_mfma_f32_16x16x32_bf16 v[68:71], v[212:215], v[172:175], v[68:71]
	v_mfma_f32_16x16x32_bf16 v[64:67], v[220:223], v[172:175], v[64:67]
	s_mov_b32 m0, s28
	s_barrier
	ds_read_b128 v[144:147], v197 offset:16384
	ds_read_b128 v[148:151], v197 offset:17408
	ds_read_b128 v[152:155], v197 offset:18432
	ds_read_b128 v[156:159], v197 offset:19456
	ds_read_b128 v[160:163], v197 offset:20480
	ds_read_b128 v[164:167], v197 offset:21504
	ds_read_b128 v[168:171], v197 offset:22528
	ds_read_b128 v[172:175], v197 offset:23552
	global_load_lds_dwordx4 v176, s[76:77]
	s_mov_b32 m0, s34
	s_nop 0
	global_load_lds_dwordx4 v184, s[76:77]
	s_barrier
	s_waitcnt lgkmcnt(0)
	s_waitcnt lgkmcnt(0)
	v_mfma_f32_16x16x32_bf16 v[60:63], v[128:131], v[144:147], v[60:63]
	v_mfma_f32_16x16x32_bf16 v[56:59], v[136:139], v[144:147], v[56:59]
	v_mfma_f32_16x16x32_bf16 v[52:55], v[128:131], v[152:155], v[52:55]
	v_mfma_f32_16x16x32_bf16 v[40:43], v[136:139], v[152:155], v[40:43]
	v_mfma_f32_16x16x32_bf16 v[36:39], v[128:131], v[160:163], v[36:39]
	v_mfma_f32_16x16x32_bf16 v[16:19], v[136:139], v[160:163], v[16:19]
	v_mfma_f32_16x16x32_bf16 v[12:15], v[128:131], v[168:171], v[12:15]
	v_mfma_f32_16x16x32_bf16 v[0:3], v[136:139], v[168:171], v[0:3]
	v_mfma_f32_16x16x32_bf16 v[60:63], v[132:135], v[148:151], v[60:63]
	v_mfma_f32_16x16x32_bf16 v[56:59], v[140:143], v[148:151], v[56:59]
	v_mfma_f32_16x16x32_bf16 v[52:55], v[132:135], v[156:159], v[52:55]
	v_mfma_f32_16x16x32_bf16 v[40:43], v[140:143], v[156:159], v[40:43]
	v_mfma_f32_16x16x32_bf16 v[36:39], v[132:135], v[164:167], v[36:39]
	v_mfma_f32_16x16x32_bf16 v[16:19], v[140:143], v[164:167], v[16:19]
	v_mfma_f32_16x16x32_bf16 v[12:15], v[132:135], v[172:175], v[12:15]
	v_mfma_f32_16x16x32_bf16 v[0:3], v[140:143], v[172:175], v[0:3]
	s_barrier
	s_add_u32 s78, s78, s46
	s_addc_u32 s79, s79, 0
	s_add_u32 vcc_lo, s78, 0x80
	s_addc_u32 vcc_hi, s79, 0
	s_add_i32 s82, s95, s27
	s_mov_b32 m0, s82
	s_nop 0
	global_load_lds_dwordx4 v178, s[78:79]
	s_add_i32 m0, s82, 0x2000
	s_nop 0
	global_load_lds_dwordx4 v186, s[78:79]
	s_waitcnt vmcnt(6)
	s_barrier
; #define PG8_STAGE(bufoff, gbase, voff) do { _Pragma("unroll") for (int _i = 0; _i < 2; ++_i) \
;         __builtin_amdgcn_global_load_lds((const unsigned*)((const char*)(gbase) + (voff)[_i]), (LAS unsigned*)(lds + (bufoff) + ldsw + _i * 8192), 16, 0, 0); } while (0)
; #define PG8_LDA(dst, b, h) do { _Pragma("unroll") for (int m = 0; m < 4; ++m) _Pragma("unroll") for (int k = 0; k < 2; ++k) dst[m][k] = *(const LAS bf16x8*)(lds + PG8_SA(b, h) + aoff + m * 2048 + k * 1024); } while (0)
; #define PG8_LDB(dst, b, h) do { _Pragma("unroll") for (int n = 0; n < 2; ++n) _Pragma("unroll") for (int k = 0; k < 2; ++k) dst[n][k] = *(const LAS bf16x8*)(lds + PG8_SB(b, h) + boff + n * 2048 + k * 1024); } while (0)
; #define PG8_MMA(ai, bj, At, Bt) do { __builtin_amdgcn_s_setprio(1); _Pragma("unroll") for (int m = 0; m < 4; ++m) _Pragma("unroll") for (int n = 0; n < 2; ++n) _Pragma("unroll") for (int k = 0; k < 2; ++k) \
;         acc[ai][bj][m][n] = __builtin_amdgcn_mfma_f32_16x16x32_bf16(Bt[n][k], At[m][k], acc[ai][bj][m][n], 0, 0, 0); __builtin_amdgcn_s_setprio(0); } while (0)
; #define PG8_WAIT_V(n) asm volatile("s_waitcnt vmcnt(" #n ")" ::: "memory")
; #define PG8_WAIT_L(n) asm volatile("s_waitcnt lgkmcnt(" #n ")" ::: "memory")
; #define PG8_BAR __builtin_amdgcn_s_barrier()
; #define PG8_SCHED __builtin_amdgcn_sched_barrier(0)
; template <class F>
; DI void gemm_phase(const int tid, LAS unsigned char* lds, const bf16_t* Ap, int lda, const bf16_t* Bp, int ldb, int M, int N, int K, int G, int c, bool direct, const F& E) {
;     ...
;             PG8_WAIT_V(6); PG8_BAR; PG8_MMA(1, 1, At, B1); PG8_BAR;
;             PG8_LDB(B0, 1, 0); PG8_SCHED; PG8_LDA(At, 1, 0); PG8_STAGE(PG8_SA(0, 1), a2 + hsA, voffA);
;             PG8_WAIT_L(8); PG8_BAR; PG8_WAIT_L(0); PG8_MMA(0, 0, At, B0); PG8_BAR; PG8_SCHED;
;             PG8_LDB(B1, 1, 1); PG8_STAGE(PG8_SB(1, 0), b3, voffB);
;             PG8_BAR; PG8_WAIT_L(0); PG8_MMA(0, 1, At, B1); PG8_BAR;
;             PG8_LDA(At, 1, 1); PG8_STAGE(PG8_SA(1, 0), a3, voffA);
;             PG8_BAR; PG8_WAIT_L(0); PG8_MMA(1, 0, At, B0); PG8_BAR; PG8_SCHED;
	v_mfma_f32_16x16x32_bf16 v[48:51], v[208:211], v[144:147], v[48:51]
	v_mfma_f32_16x16x32_bf16 v[44:47], v[216:219], v[144:147], v[44:47]
	v_mfma_f32_16x16x32_bf16 v[24:27], v[208:211], v[152:155], v[24:27]
	v_mfma_f32_16x16x32_bf16 v[20:23], v[216:219], v[152:155], v[20:23]
	v_mfma_f32_16x16x32_bf16 v[28:31], v[208:211], v[160:163], v[28:31]
	v_mfma_f32_16x16x32_bf16 v[32:35], v[216:219], v[160:163], v[32:35]
	v_mfma_f32_16x16x32_bf16 v[8:11], v[208:211], v[168:171], v[8:11]
	v_mfma_f32_16x16x32_bf16 v[4:7], v[216:219], v[168:171], v[4:7]
	v_mfma_f32_16x16x32_bf16 v[48:51], v[212:215], v[148:151], v[48:51]
	v_mfma_f32_16x16x32_bf16 v[44:47], v[220:223], v[148:151], v[44:47]
	v_mfma_f32_16x16x32_bf16 v[24:27], v[212:215], v[156:159], v[24:27]
	v_mfma_f32_16x16x32_bf16 v[20:23], v[220:223], v[156:159], v[20:23]
	v_mfma_f32_16x16x32_bf16 v[28:31], v[212:215], v[164:167], v[28:31]
	v_mfma_f32_16x16x32_bf16 v[32:35], v[220:223], v[164:167], v[32:35]
	v_mfma_f32_16x16x32_bf16 v[8:11], v[212:215], v[172:175], v[8:11]
	v_mfma_f32_16x16x32_bf16 v[4:7], v[220:223], v[172:175], v[4:7]
	s_add_i32 s78, 0, 0x18000
	v_add_u32_e32 v140, s78, v189
	s_barrier
	ds_read_b128 v[128:131], v140
	ds_read_b128 v[132:135], v140 offset:1024
	ds_read_b128 v[136:139], v140 offset:2048
	ds_read_b128 v[140:143], v140 offset:3072
	s_add_u32 s76, s76, s24
	s_addc_u32 s77, s77, 0
	s_mov_b32 m0, s60
	ds_read_b128 v[144:147], v197 offset:32768
	ds_read_b128 v[148:151], v197 offset:33792
	ds_read_b128 v[152:155], v197 offset:34816
	ds_read_b128 v[156:159], v197 offset:35840
	ds_read_b128 v[160:163], v197 offset:36864
	ds_read_b128 v[164:167], v197 offset:37888
	ds_read_b128 v[168:171], v197 offset:38912
	ds_read_b128 v[172:175], v197 offset:39936
	global_load_lds_dwordx4 v176, s[76:77]
	s_mov_b32 m0, s61
	s_nop 0
	global_load_lds_dwordx4 v184, s[76:77]
	s_waitcnt lgkmcnt(8)
	s_barrier
	s_waitcnt lgkmcnt(0)
	s_waitcnt lgkmcnt(0)
	v_mfma_f32_16x16x32_bf16 v[124:127], v[128:131], v[144:147], v[124:127]
	v_mfma_f32_16x16x32_bf16 v[120:123], v[136:139], v[144:147], v[120:123]
	v_mfma_f32_16x16x32_bf16 v[116:119], v[128:131], v[152:155], v[116:119]
	v_mfma_f32_16x16x32_bf16 v[104:107], v[136:139], v[152:155], v[104:107]
	v_mfma_f32_16x16x32_bf16 v[100:103], v[128:131], v[160:163], v[100:103]
	v_mfma_f32_16x16x32_bf16 v[88:91], v[136:139], v[160:163], v[88:91]
	v_mfma_f32_16x16x32_bf16 v[84:87], v[128:131], v[168:171], v[84:87]
	v_mfma_f32_16x16x32_bf16 v[72:75], v[136:139], v[168:171], v[72:75]
	v_mfma_f32_16x16x32_bf16 v[124:127], v[132:135], v[148:151], v[124:127]
	v_mfma_f32_16x16x32_bf16 v[120:123], v[140:143], v[148:151], v[120:123]
	v_mfma_f32_16x16x32_bf16 v[116:119], v[132:135], v[156:159], v[116:119]
	v_mfma_f32_16x16x32_bf16 v[104:107], v[140:143], v[156:159], v[104:107]
	v_mfma_f32_16x16x32_bf16 v[100:103], v[132:135], v[164:167], v[100:103]
	v_mfma_f32_16x16x32_bf16 v[88:91], v[140:143], v[164:167], v[88:91]
	v_mfma_f32_16x16x32_bf16 v[84:87], v[132:135], v[172:175], v[84:87]
	v_mfma_f32_16x16x32_bf16 v[72:75], v[140:143], v[172:175], v[72:75]
	s_barrier
	s_add_i32 s76, 0, 0x1c000
	s_add_i32 s77, s78, s27
	v_add_u32_e32 v180, s76, v189
	s_mov_b32 m0, s77
	ds_read_b128 v[208:211], v180
	ds_read_b128 v[212:215], v180 offset:1024
	ds_read_b128 v[216:219], v180 offset:2048
	ds_read_b128 v[220:223], v180 offset:3072
	global_load_lds_dwordx4 v178, s[98:99]
	s_add_i32 m0, s77, 0x2000
	s_nop 0
	global_load_lds_dwordx4 v186, s[98:99]
	s_barrier
	s_waitcnt lgkmcnt(0)
	s_waitcnt lgkmcnt(0)
	v_mfma_f32_16x16x32_bf16 v[112:115], v[208:211], v[144:147], v[112:115]
	v_mfma_f32_16x16x32_bf16 v[108:111], v[216:219], v[144:147], v[108:111]
	v_mfma_f32_16x16x32_bf16 v[96:99], v[208:211], v[152:155], v[96:99]
	v_mfma_f32_16x16x32_bf16 v[92:95], v[216:219], v[152:155], v[92:95]
	v_mfma_f32_16x16x32_bf16 v[80:83], v[208:211], v[160:163], v[80:83]
	v_mfma_f32_16x16x32_bf16 v[76:79], v[216:219], v[160:163], v[76:79]
	v_mfma_f32_16x16x32_bf16 v[68:71], v[208:211], v[168:171], v[68:71]
	v_mfma_f32_16x16x32_bf16 v[64:67], v[216:219], v[168:171], v[64:67]
	v_mfma_f32_16x16x32_bf16 v[112:115], v[212:215], v[148:151], v[112:115]
	v_mfma_f32_16x16x32_bf16 v[108:111], v[220:223], v[148:151], v[108:111]
	v_mfma_f32_16x16x32_bf16 v[96:99], v[212:215], v[156:159], v[96:99]
	v_mfma_f32_16x16x32_bf16 v[92:95], v[220:223], v[156:159], v[92:95]
	v_mfma_f32_16x16x32_bf16 v[80:83], v[212:215], v[164:167], v[80:83]
	v_mfma_f32_16x16x32_bf16 v[76:79], v[220:223], v[164:167], v[76:79]
	v_mfma_f32_16x16x32_bf16 v[68:71], v[212:215], v[172:175], v[68:71]
	v_mfma_f32_16x16x32_bf16 v[64:67], v[220:223], v[172:175], v[64:67]
	s_mov_b32 m0, s62
	s_barrier
	ds_read_b128 v[144:147], v197 offset:49152
	ds_read_b128 v[148:151], v197 offset:50176
	ds_read_b128 v[152:155], v197 offset:51200
	ds_read_b128 v[156:159], v197 offset:52224
	ds_read_b128 v[160:163], v197 offset:53248
	ds_read_b128 v[164:167], v197 offset:54272
	ds_read_b128 v[168:171], v197 offset:55296
	ds_read_b128 v[172:175], v197 offset:56320
	global_load_lds_dwordx4 v176, s[100:101]
	s_mov_b32 m0, s63
	s_nop 0
	global_load_lds_dwordx4 v184, s[100:101]
	s_barrier
; #define PG8_STAGE(bufoff, gbase, voff) do { _Pragma("unroll") for (int _i = 0; _i < 2; ++_i) \
;         __builtin_amdgcn_global_load_lds((const unsigned*)((const char*)(gbase) + (voff)[_i]), (LAS unsigned*)(lds + (bufoff) + ldsw + _i * 8192), 16, 0, 0); } while (0)
; #define PG8_MMA(ai, bj, At, Bt) do { __builtin_amdgcn_s_setprio(1); _Pragma("unroll") for (int m = 0; m < 4; ++m) _Pragma("unroll") for (int n = 0; n < 2; ++n) _Pragma("unroll") for (int k = 0; k < 2; ++k) \
;         acc[ai][bj][m][n] = __builtin_amdgcn_mfma_f32_16x16x32_bf16(Bt[n][k], At[m][k], acc[ai][bj][m][n], 0, 0, 0); __builtin_amdgcn_s_setprio(0); } while (0)
; #define PG8_WAIT_V(n) asm volatile("s_waitcnt vmcnt(" #n ")" ::: "memory")
; #define PG8_WAIT_L(n) asm volatile("s_waitcnt lgkmcnt(" #n ")" ::: "memory")
; #define PG8_BAR __builtin_amdgcn_s_barrier()
; #define PG8_SCHED __builtin_amdgcn_sched_barrier(0)
; template <class F>
; DI void gemm_phase(const int tid, LAS unsigned char* lds, const bf16_t* Ap, int lda, const bf16_t* Bp, int ldb, int M, int N, int K, int G, int c, bool direct, const F& E) {
;     ...
;             PG8_BAR; PG8_WAIT_L(0); PG8_MMA(1, 0, At, B0); PG8_BAR; PG8_SCHED;
;             PG8_STAGE(PG8_SB(1, 1), b3 + hsB, voffB);
;             PG8_WAIT_V(6); PG8_BAR; PG8_MMA(1, 1, At, B1); PG8_BAR;
;         }
;         if (E.kind == 7  ) E.fused(acc, cur.pm, cur.pn, wr, wc, fr, fq);
;         else if (E.kind == 3  ) {
; DI void Epi::fused(const f32x4 (&acc)[2][2][4][2], int pm, int pn, int wr, int wc, int fr, int fq) const {
;     ...
;         const int ncol = pn * 256 + bj * 128 + wc * 32 + 8 * fq, j0 = (ncol >> 3) * 4;
;         const f32x4 wa0 = *(const f32x4*)(E.cf0 + j0), wa1 = *(const f32x4*)(E.cf0 + FF2 + j0), wa2 = *(const f32x4*)(E.cf0 + 2 * FF2 + j0);
;         const f32x4 wb0 = *(const f32x4*)(E.cf0 + FFH + j0), wb1 = *(const f32x4*)(E.cf0 + FF2 + FFH + j0), wb2 = *(const f32x4*)(E.cf0 + 2 * FF2 + FFH + j0);
;         const f32x4 ba = *(const f32x4*)(E.cf1 + j0), bb = *(const f32x4*)(E.cf1 + FFH + j0);
; #pragma unroll
;         for (int ai = 0; ai < 2; ++ai) {
;             f32x4 pa = (f32x4){0.f, 0.f, 0.f, 0.f}, pb = pa;
; #pragma unroll
;             for (int m = 0; m < 4; ++m) {
;                 const f32x4 ca = acc[ai][bj][m][0], cb = acc[ai][bj][m][1];
;                 const int row = pm * 256 + ai * 128 + wr * 64 + m * 16 + fr;
	s_waitcnt lgkmcnt(0)
	s_waitcnt lgkmcnt(0)
	v_mfma_f32_16x16x32_bf16 v[60:63], v[128:131], v[144:147], v[60:63]
	v_mfma_f32_16x16x32_bf16 v[56:59], v[136:139], v[144:147], v[56:59]
	v_mfma_f32_16x16x32_bf16 v[52:55], v[128:131], v[152:155], v[52:55]
	v_mfma_f32_16x16x32_bf16 v[40:43], v[136:139], v[152:155], v[40:43]
	v_mfma_f32_16x16x32_bf16 v[36:39], v[128:131], v[160:163], v[36:39]
	v_mfma_f32_16x16x32_bf16 v[16:19], v[136:139], v[160:163], v[16:19]
	v_mfma_f32_16x16x32_bf16 v[12:15], v[128:131], v[168:171], v[12:15]
	v_mfma_f32_16x16x32_bf16 v[0:3], v[136:139], v[168:171], v[0:3]
	v_mfma_f32_16x16x32_bf16 v[60:63], v[132:135], v[148:151], v[60:63]
	v_mfma_f32_16x16x32_bf16 v[56:59], v[140:143], v[148:151], v[56:59]
	v_mfma_f32_16x16x32_bf16 v[52:55], v[132:135], v[156:159], v[52:55]
	v_mfma_f32_16x16x32_bf16 v[40:43], v[140:143], v[156:159], v[40:43]
	v_mfma_f32_16x16x32_bf16 v[36:39], v[132:135], v[164:167], v[36:39]
	v_mfma_f32_16x16x32_bf16 v[16:19], v[140:143], v[164:167], v[16:19]
	v_mfma_f32_16x16x32_bf16 v[12:15], v[132:135], v[172:175], v[12:15]
	v_mfma_f32_16x16x32_bf16 v[0:3], v[140:143], v[172:175], v[0:3]
	s_barrier
	s_add_i32 s76, s76, s27
	s_mov_b32 m0, s76
	s_nop 0
	global_load_lds_dwordx4 v178, vcc
	s_add_i32 m0, s76, 0x2000
	s_nop 0
	global_load_lds_dwordx4 v186, vcc
	s_waitcnt vmcnt(6)
	s_barrier
	v_mfma_f32_16x16x32_bf16 v[48:51], v[208:211], v[144:147], v[48:51]
	v_mfma_f32_16x16x32_bf16 v[44:47], v[216:219], v[144:147], v[44:47]
	v_mfma_f32_16x16x32_bf16 v[24:27], v[208:211], v[152:155], v[24:27]
	v_mfma_f32_16x16x32_bf16 v[20:23], v[216:219], v[152:155], v[20:23]
	v_mfma_f32_16x16x32_bf16 v[28:31], v[208:211], v[160:163], v[28:31]
	v_mfma_f32_16x16x32_bf16 v[32:35], v[216:219], v[160:163], v[32:35]
	v_mfma_f32_16x16x32_bf16 v[8:11], v[208:211], v[168:171], v[8:11]
	v_mfma_f32_16x16x32_bf16 v[4:7], v[216:219], v[168:171], v[4:7]
	v_mfma_f32_16x16x32_bf16 v[48:51], v[212:215], v[148:151], v[48:51]
	v_mfma_f32_16x16x32_bf16 v[44:47], v[220:223], v[148:151], v[44:47]
	v_mfma_f32_16x16x32_bf16 v[24:27], v[212:215], v[156:159], v[24:27]
	v_mfma_f32_16x16x32_bf16 v[20:23], v[220:223], v[156:159], v[20:23]
	v_mfma_f32_16x16x32_bf16 v[28:31], v[212:215], v[164:167], v[28:31]
	v_mfma_f32_16x16x32_bf16 v[32:35], v[220:223], v[164:167], v[32:35]
	v_mfma_f32_16x16x32_bf16 v[8:11], v[212:215], v[172:175], v[8:11]
	v_mfma_f32_16x16x32_bf16 v[4:7], v[220:223], v[172:175], v[4:7]
	s_add_u32 s74, s74, 0x100
	s_addc_u32 s75, s75, 0
	s_add_u32 s71, s71, 0x100
	s_addc_u32 s80, s80, 0
	s_cmp_ge_u32 s81, s26
	s_mov_b32 s76, s81
	s_barrier
	s_cbranch_scc0 .LBB0_657
	s_cmp_eq_u32 s92, 1
	s_cbranch_scc1 .Lresid_epi
	s_mov_b64 s[76:77], -1
	s_mov_b64 s[74:75], 0
	s_cmp_lt_i32 s92, 3
	s_mov_b64 s[78:79], 0
	s_cbranch_scc1 .LBB0_688
	s_cmp_gt_i32 s92, 6
	s_mov_b64 s[78:79], -1
	s_cbranch_scc0 .LBB0_685
	v_lshl_or_b32 v240, s70, 8, v194
	v_mov_b32_e32 v241, 0
	s_lshl_b32 s71, s36, 8
	v_readlane_b32 s76, v255, 16
	s_nop 3
	s_add_i32 s71, s71, s76
	v_or_b32_e32 v199, s71, v188
	v_lshlrev_b32_e32 v238, 1, v240
	v_mov_b32_e32 v239, 0
	v_lshl_add_u64 v[136:137], s[22:23], 0, v[238:239]
	global_load_dwordx4 v[136:139], v[136:137], off
	v_readlane_b32 s76, v254, 54
	v_readlane_b32 s77, v254, 55
	s_nop 1
	v_lshl_add_u64 v[140:141], s[76:77], 0, v[238:239]
	global_load_dwordx4 v[140:143], v[140:141], off
	v_readlane_b32 s76, v254, 56
	v_readlane_b32 s77, v254, 57
	s_nop 1
	v_lshl_add_u64 v[152:153], s[76:77], 0, v[238:239]
	global_load_dwordx4 v[152:155], v[152:153], off
	v_readlane_b32 s76, v255, 4
	v_readlane_b32 s77, v255, 5
	s_nop 1
	v_lshl_add_u64 v[128:129], s[76:77], 0, v[238:239]
	global_load_dwordx4 v[128:131], v[128:129], off
	v_readlane_b32 s76, v255, 6
	v_readlane_b32 s77, v255, 7
	s_nop 1
	v_lshl_add_u64 v[132:133], s[76:77], 0, v[238:239]
	global_load_dwordx4 v[132:135], v[132:133], off
	v_readlane_b32 s76, v255, 8
	v_readlane_b32 s77, v255, 9
	s_nop 1
	v_lshl_add_u64 v[144:145], s[76:77], 0, v[238:239]
	global_load_dwordx4 v[144:147], v[144:145], off
	v_readlane_b32 s76, v254, 49
	v_readlane_b32 s77, v254, 50
	s_nop 1
	v_lshl_add_u64 v[156:157], s[76:77], 0, v[238:239]
	global_load_dwordx4 v[156:159], v[156:157], off
	v_lshl_add_u64 v[148:149], s[72:73], 0, v[238:239]
	global_load_dwordx4 v[148:151], v[148:149], off
	v_mov_b32_e32 v228, v199
	v_mov_b64_e32 v[224:225], s[12:13]
	s_movk_i32 s80, 0x1600
	v_mad_i64_i32 v[224:225], s[78:79], v228, s80, v[224:225]
	v_mov_b32_e32 v228, v240
	v_mov_b32_e32 v229, 0
	v_lshl_add_u64 v[224:225], v[228:229], 0, v[224:225]
	s_waitcnt vmcnt(0)
; DI float silu_fast(float x) { return x * __builtin_amdgcn_rcpf(1.f + __expf(-x)); }
; template <int CTRL> DI float dppf(float v) { return __builtin_bit_cast(float, __builtin_amdgcn_update_dpp(0, __builtin_bit_cast(int, v), CTRL, 0xf, 0xf, true)); }
; DI void Epi::fused(const f32x4 (&acc)[2][2][4][2], int pm, int pn, int wr, int wc, int fr, int fq) const {
;     ...
;                 const f32x4 ca = acc[ai][bj][m][0], cb = acc[ai][bj][m][1];
;                 const int row = pm * 256 + ai * 128 + wr * 64 + m * 16 + fr;
;                 float o[4];
; #pragma unroll
;                 for (int e = 0; e < 4; ++e) {
;                     const float a1 = dppf<0x111>(ca[e]) + dppf<0x10F>(pa[e]), a2 = dppf<0x112>(ca[e]) + dppf<0x10E>(pa[e]);
;                     const float b1 = dppf<0x111>(cb[e]) + dppf<0x10F>(pb[e]), b2 = dppf<0x112>(cb[e]) + dppf<0x10E>(pb[e]);
;                     const float ya = fmaf(wa0[e], a2, fmaf(wa1[e], a1, fmaf(wa2[e], ca[e], ba[e])));
;                     const float yb = fmaf(wb0[e], b2, fmaf(wb1[e], b1, fmaf(wb2[e], cb[e], bb[e])));
;                     o[e] = silu_fast(ya) * yb; }
;                 if (m > 0 || fr >= 2) { u32x2 w; w.x = pk2(o[0], o[1]); w.y = pk2(o[2], o[3]); *(u32x2*)(E.d0 + (size_t)row * FFH + j0) = w; }
;                 if ((m == 0 && fr < 2) || (m == 3 && fr >= 14)) { float* hb = E.f0 + ((size_t)(row >> 6) * 4 + (m == 0 ? fr : fr - 12)) * FF2 + ncol; *(f32x4*)hb = ca; *(f32x4*)(hb + 4) = cb; }
;                 pa = ca; pb = cb;
	v_fma_f32 v160, v152, v124, v156
	v_fma_f32 v161, v153, v125, v157
	v_fma_f32 v162, v154, v126, v158
	v_fma_f32 v163, v155, v127, v159
	v_fma_f32 v164, v144, v120, v148
	v_fma_f32 v165, v145, v121, v149
	v_fma_f32 v166, v146, v122, v150
	v_fma_f32 v167, v147, v123, v151
	v_fmac_f32_dpp v160, v124, v140 row_shr:1 row_mask:0xf bank_mask:0xf
	v_fmac_f32_dpp v161, v125, v141 row_shr:1 row_mask:0xf bank_mask:0xf
	v_fmac_f32_dpp v162, v126, v142 row_shr:1 row_mask:0xf bank_mask:0xf
	v_fmac_f32_dpp v163, v127, v143 row_shr:1 row_mask:0xf bank_mask:0xf
	v_fmac_f32_dpp v164, v120, v132 row_shr:1 row_mask:0xf bank_mask:0xf
	v_fmac_f32_dpp v165, v121, v133 row_shr:1 row_mask:0xf bank_mask:0xf
	v_fmac_f32_dpp v166, v122, v134 row_shr:1 row_mask:0xf bank_mask:0xf
	v_fmac_f32_dpp v167, v123, v135 row_shr:1 row_mask:0xf bank_mask:0xf
	v_fmac_f32_dpp v160, v124, v136 row_shr:2 row_mask:0xf bank_mask:0xf
	v_fmac_f32_dpp v161, v125, v137 row_shr:2 row_mask:0xf bank_mask:0xf
	v_fmac_f32_dpp v162, v126, v138 row_shr:2 row_mask:0xf bank_mask:0xf
	v_fmac_f32_dpp v163, v127, v139 row_shr:2 row_mask:0xf bank_mask:0xf
	v_fmac_f32_dpp v164, v120, v128 row_shr:2 row_mask:0xf bank_mask:0xf
	v_fmac_f32_dpp v165, v121, v129 row_shr:2 row_mask:0xf bank_mask:0xf
	v_fmac_f32_dpp v166, v122, v130 row_shr:2 row_mask:0xf bank_mask:0xf
	v_fmac_f32_dpp v167, v123, v131 row_shr:2 row_mask:0xf bank_mask:0xf
	v_mul_f32_e32 v168, 0xbfb8aa3b, v160
	v_mul_f32_e32 v169, 0xbfb8aa3b, v161
	v_mul_f32_e32 v170, 0xbfb8aa3b, v162
	v_mul_f32_e32 v171, 0xbfb8aa3b, v163
	v_exp_f32_e32 v168, v168
	v_exp_f32_e32 v169, v169
	v_exp_f32_e32 v170, v170
	v_exp_f32_e32 v171, v171
	v_add_f32_e32 v168, 1.0, v168
	v_add_f32_e32 v169, 1.0, v169
	v_add_f32_e32 v170, 1.0, v170
	v_add_f32_e32 v171, 1.0, v171
	v_rcp_f32_e32 v168, v168
	v_rcp_f32_e32 v169, v169
	v_rcp_f32_e32 v170, v170
	v_rcp_f32_e32 v171, v171
	v_mov_b64_e32 v[174:175], v[224:225]
	v_mul_f32_e32 v160, v160, v168
	v_mul_f32_e32 v161, v161, v169
	v_mul_f32_e32 v162, v162, v170
	v_mul_f32_e32 v163, v163, v171
	v_mul_f32_e32 v160, v164, v160
	v_mul_f32_e32 v161, v165, v161
	v_mul_f32_e32 v162, v166, v162
	v_mul_f32_e32 v163, v167, v163
	v_cvt_pk_bf16_f32 v172, v160, v161
	v_cvt_pk_bf16_f32 v173, v162, v163
	s_and_saveexec_b64 s[76:77], s[38:39]
	global_store_dwordx2 v[174:175], v[172:173], off
	s_or_b64 exec, exec, s[76:77]
	s_ashr_i32 s80, s71, 6
	s_lshl_b32 s80, s80, 2
	v_add_u32_e32 v226, s80, v188
	v_mov_b64_e32 v[174:175], s[8:9]
	s_movk_i32 s80, 0x5800
	v_mad_i64_i32 v[174:175], s[78:79], v226, s80, v[174:175]
	v_lshl_add_u64 v[174:175], v[228:229], 2, v[174:175]
	s_and_saveexec_b64 s[76:77], s[40:41]
	global_store_dwordx4 v[174:175], v[124:127], off
	global_store_dwordx4 v[174:175], v[120:123], off offset:16
	s_or_b64 exec, exec, s[76:77]
	v_fma_f32 v208, v152, v116, v156
	v_fma_f32 v209, v153, v117, v157
	v_fma_f32 v210, v154, v118, v158
	v_fma_f32 v211, v155, v119, v159
	v_fma_f32 v212, v144, v104, v148
	v_fma_f32 v213, v145, v105, v149
	v_fma_f32 v214, v146, v106, v150
	v_fma_f32 v215, v147, v107, v151
	v_fmac_f32_dpp v208, v116, v140 row_shr:1 row_mask:0xf bank_mask:0xf
	v_fmac_f32_dpp v209, v117, v141 row_shr:1 row_mask:0xf bank_mask:0xf
	v_fmac_f32_dpp v210, v118, v142 row_shr:1 row_mask:0xf bank_mask:0xf
	v_fmac_f32_dpp v211, v119, v143 row_shr:1 row_mask:0xf bank_mask:0xf
	v_fmac_f32_dpp v212, v104, v132 row_shr:1 row_mask:0xf bank_mask:0xf
	v_fmac_f32_dpp v213, v105, v133 row_shr:1 row_mask:0xf bank_mask:0xf
	v_fmac_f32_dpp v214, v106, v134 row_shr:1 row_mask:0xf bank_mask:0xf
	v_fmac_f32_dpp v215, v107, v135 row_shr:1 row_mask:0xf bank_mask:0xf
	v_fmac_f32_dpp v208, v124, v140 row_shl:15 row_mask:0xf bank_mask:0xf
	v_fmac_f32_dpp v209, v125, v141 row_shl:15 row_mask:0xf bank_mask:0xf
	v_fmac_f32_dpp v210, v126, v142 row_shl:15 row_mask:0xf bank_mask:0xf
	v_fmac_f32_dpp v211, v127, v143 row_shl:15 row_mask:0xf bank_mask:0xf
	v_fmac_f32_dpp v212, v120, v132 row_shl:15 row_mask:0xf bank_mask:0xf
	v_fmac_f32_dpp v213, v121, v133 row_shl:15 row_mask:0xf bank_mask:0xf
	v_fmac_f32_dpp v214, v122, v134 row_shl:15 row_mask:0xf bank_mask:0xf
	v_fmac_f32_dpp v215, v123, v135 row_shl:15 row_mask:0xf bank_mask:0xf
	v_fmac_f32_dpp v208, v116, v136 row_shr:2 row_mask:0xf bank_mask:0xf
	v_fmac_f32_dpp v209, v117, v137 row_shr:2 row_mask:0xf bank_mask:0xf
	v_fmac_f32_dpp v210, v118, v138 row_shr:2 row_mask:0xf bank_mask:0xf
	v_fmac_f32_dpp v211, v119, v139 row_shr:2 row_mask:0xf bank_mask:0xf
	v_fmac_f32_dpp v212, v104, v128 row_shr:2 row_mask:0xf bank_mask:0xf
	v_fmac_f32_dpp v213, v105, v129 row_shr:2 row_mask:0xf bank_mask:0xf
	v_fmac_f32_dpp v214, v106, v130 row_shr:2 row_mask:0xf bank_mask:0xf
	v_fmac_f32_dpp v215, v107, v131 row_shr:2 row_mask:0xf bank_mask:0xf
	v_fmac_f32_dpp v208, v124, v136 row_shl:14 row_mask:0xf bank_mask:0xf
	v_fmac_f32_dpp v209, v125, v137 row_shl:14 row_mask:0xf bank_mask:0xf
	v_fmac_f32_dpp v210, v126, v138 row_shl:14 row_mask:0xf bank_mask:0xf
	v_fmac_f32_dpp v211, v127, v139 row_shl:14 row_mask:0xf bank_mask:0xf
	v_fmac_f32_dpp v212, v120, v128 row_shl:14 row_mask:0xf bank_mask:0xf
	v_fmac_f32_dpp v213, v121, v129 row_shl:14 row_mask:0xf bank_mask:0xf
	v_fmac_f32_dpp v214, v122, v130 row_shl:14 row_mask:0xf bank_mask:0xf
	v_fmac_f32_dpp v215, v123, v131 row_shl:14 row_mask:0xf bank_mask:0xf
	v_mul_f32_e32 v216, 0xbfb8aa3b, v208
	v_mul_f32_e32 v217, 0xbfb8aa3b, v209
	v_mul_f32_e32 v218, 0xbfb8aa3b, v210
	v_mul_f32_e32 v219, 0xbfb8aa3b, v211
	v_exp_f32_e32 v216, v216
	v_exp_f32_e32 v217, v217
	v_exp_f32_e32 v218, v218
	v_exp_f32_e32 v219, v219
	v_add_f32_e32 v216, 1.0, v216
	v_add_f32_e32 v217, 1.0, v217
; DI float silu_fast(float x) { return x * __builtin_amdgcn_rcpf(1.f + __expf(-x)); }
; template <int CTRL> DI float dppf(float v) { return __builtin_bit_cast(float, __builtin_amdgcn_update_dpp(0, __builtin_bit_cast(int, v), CTRL, 0xf, 0xf, true)); }
; DI void Epi::fused(const f32x4 (&acc)[2][2][4][2], int pm, int pn, int wr, int wc, int fr, int fq) const {
;     ...
;                 for (int e = 0; e < 4; ++e) {
;                     const float a1 = dppf<0x111>(ca[e]) + dppf<0x10F>(pa[e]), a2 = dppf<0x112>(ca[e]) + dppf<0x10E>(pa[e]);
;                     const float b1 = dppf<0x111>(cb[e]) + dppf<0x10F>(pb[e]), b2 = dppf<0x112>(cb[e]) + dppf<0x10E>(pb[e]);
;                     const float ya = fmaf(wa0[e], a2, fmaf(wa1[e], a1, fmaf(wa2[e], ca[e], ba[e])));
;                     const float yb = fmaf(wb0[e], b2, fmaf(wb1[e], b1, fmaf(wb2[e], cb[e], bb[e])));
;                     o[e] = silu_fast(ya) * yb; }
;                 if (m > 0 || fr >= 2) { u32x2 w; w.x = pk2(o[0], o[1]); w.y = pk2(o[2], o[3]); *(u32x2*)(E.d0 + (size_t)row * FFH + j0) = w; }
;                 if ((m == 0 && fr < 2) || (m == 3 && fr >= 14)) { float* hb = E.f0 + ((size_t)(row >> 6) * 4 + (m == 0 ? fr : fr - 12)) * FF2 + ncol; *(f32x4*)hb = ca; *(f32x4*)(hb + 4) = cb; }
;                 pa = ca; pb = cb;
	v_add_f32_e32 v218, 1.0, v218
	v_add_f32_e32 v219, 1.0, v219
	v_rcp_f32_e32 v216, v216
	v_rcp_f32_e32 v217, v217
	v_rcp_f32_e32 v218, v218
	v_rcp_f32_e32 v219, v219
	s_mov_b32 s80, 0x16000
	s_mov_b32 s81, 0
	v_lshl_add_u64 v[222:223], v[224:225], 0, s[80:81]
	v_mul_f32_e32 v208, v208, v216
	v_mul_f32_e32 v209, v209, v217
	v_mul_f32_e32 v210, v210, v218
	v_mul_f32_e32 v211, v211, v219
	v_mul_f32_e32 v208, v212, v208
	v_mul_f32_e32 v209, v213, v209
	v_mul_f32_e32 v210, v214, v210
	v_mul_f32_e32 v211, v215, v211
	v_cvt_pk_bf16_f32 v220, v208, v209
	v_cvt_pk_bf16_f32 v221, v210, v211
	global_store_dwordx2 v[222:223], v[220:221], off
	v_fma_f32 v160, v152, v100, v156
	v_fma_f32 v161, v153, v101, v157
	v_fma_f32 v162, v154, v102, v158
	v_fma_f32 v163, v155, v103, v159
	v_fma_f32 v164, v144, v88, v148
	v_fma_f32 v165, v145, v89, v149
	v_fma_f32 v166, v146, v90, v150
	v_fma_f32 v167, v147, v91, v151
	v_fmac_f32_dpp v160, v100, v140 row_shr:1 row_mask:0xf bank_mask:0xf
	v_fmac_f32_dpp v161, v101, v141 row_shr:1 row_mask:0xf bank_mask:0xf
	v_fmac_f32_dpp v162, v102, v142 row_shr:1 row_mask:0xf bank_mask:0xf
	v_fmac_f32_dpp v163, v103, v143 row_shr:1 row_mask:0xf bank_mask:0xf
	v_fmac_f32_dpp v164, v88, v132 row_shr:1 row_mask:0xf bank_mask:0xf
	v_fmac_f32_dpp v165, v89, v133 row_shr:1 row_mask:0xf bank_mask:0xf
	v_fmac_f32_dpp v166, v90, v134 row_shr:1 row_mask:0xf bank_mask:0xf
	v_fmac_f32_dpp v167, v91, v135 row_shr:1 row_mask:0xf bank_mask:0xf
	v_fmac_f32_dpp v160, v116, v140 row_shl:15 row_mask:0xf bank_mask:0xf
	v_fmac_f32_dpp v161, v117, v141 row_shl:15 row_mask:0xf bank_mask:0xf
	v_fmac_f32_dpp v162, v118, v142 row_shl:15 row_mask:0xf bank_mask:0xf
	v_fmac_f32_dpp v163, v119, v143 row_shl:15 row_mask:0xf bank_mask:0xf
	v_fmac_f32_dpp v164, v104, v132 row_shl:15 row_mask:0xf bank_mask:0xf
	v_fmac_f32_dpp v165, v105, v133 row_shl:15 row_mask:0xf bank_mask:0xf
	v_fmac_f32_dpp v166, v106, v134 row_shl:15 row_mask:0xf bank_mask:0xf
	v_fmac_f32_dpp v167, v107, v135 row_shl:15 row_mask:0xf bank_mask:0xf
	v_fmac_f32_dpp v160, v100, v136 row_shr:2 row_mask:0xf bank_mask:0xf
	v_fmac_f32_dpp v161, v101, v137 row_shr:2 row_mask:0xf bank_mask:0xf
	v_fmac_f32_dpp v162, v102, v138 row_shr:2 row_mask:0xf bank_mask:0xf
	v_fmac_f32_dpp v163, v103, v139 row_shr:2 row_mask:0xf bank_mask:0xf
	v_fmac_f32_dpp v164, v88, v128 row_shr:2 row_mask:0xf bank_mask:0xf
	v_fmac_f32_dpp v165, v89, v129 row_shr:2 row_mask:0xf bank_mask:0xf
	v_fmac_f32_dpp v166, v90, v130 row_shr:2 row_mask:0xf bank_mask:0xf
	v_fmac_f32_dpp v167, v91, v131 row_shr:2 row_mask:0xf bank_mask:0xf
	v_fmac_f32_dpp v160, v116, v136 row_shl:14 row_mask:0xf bank_mask:0xf
	v_fmac_f32_dpp v161, v117, v137 row_shl:14 row_mask:0xf bank_mask:0xf
	v_fmac_f32_dpp v162, v118, v138 row_shl:14 row_mask:0xf bank_mask:0xf
	v_fmac_f32_dpp v163, v119, v139 row_shl:14 row_mask:0xf bank_mask:0xf
	v_fmac_f32_dpp v164, v104, v128 row_shl:14 row_mask:0xf bank_mask:0xf
	v_fmac_f32_dpp v165, v105, v129 row_shl:14 row_mask:0xf bank_mask:0xf
	v_fmac_f32_dpp v166, v106, v130 row_shl:14 row_mask:0xf bank_mask:0xf
	v_fmac_f32_dpp v167, v107, v131 row_shl:14 row_mask:0xf bank_mask:0xf
	v_mul_f32_e32 v168, 0xbfb8aa3b, v160
	v_mul_f32_e32 v169, 0xbfb8aa3b, v161
	v_mul_f32_e32 v170, 0xbfb8aa3b, v162
	v_mul_f32_e32 v171, 0xbfb8aa3b, v163
	v_exp_f32_e32 v168, v168
	v_exp_f32_e32 v169, v169
	v_exp_f32_e32 v170, v170
	v_exp_f32_e32 v171, v171
	v_add_f32_e32 v168, 1.0, v168
	v_add_f32_e32 v169, 1.0, v169
	v_add_f32_e32 v170, 1.0, v170
	v_add_f32_e32 v171, 1.0, v171
	v_rcp_f32_e32 v168, v168
	v_rcp_f32_e32 v169, v169
	v_rcp_f32_e32 v170, v170
	v_rcp_f32_e32 v171, v171
	s_mov_b32 s80, 0x2c000
	s_mov_b32 s81, 0
	v_lshl_add_u64 v[174:175], v[224:225], 0, s[80:81]
	v_mul_f32_e32 v160, v160, v168
	v_mul_f32_e32 v161, v161, v169
	v_mul_f32_e32 v162, v162, v170
	v_mul_f32_e32 v163, v163, v171
	v_mul_f32_e32 v160, v164, v160
	v_mul_f32_e32 v161, v165, v161
	v_mul_f32_e32 v162, v166, v162
	v_mul_f32_e32 v163, v167, v163
	v_cvt_pk_bf16_f32 v172, v160, v161
	v_cvt_pk_bf16_f32 v173, v162, v163
	global_store_dwordx2 v[174:175], v[172:173], off
	v_fma_f32 v208, v152, v84, v156
	v_fma_f32 v209, v153, v85, v157
	v_fma_f32 v210, v154, v86, v158
	v_fma_f32 v211, v155, v87, v159
	v_fma_f32 v212, v144, v72, v148
	v_fma_f32 v213, v145, v73, v149
	v_fma_f32 v214, v146, v74, v150
	v_fma_f32 v215, v147, v75, v151
	v_fmac_f32_dpp v208, v84, v140 row_shr:1 row_mask:0xf bank_mask:0xf
	v_fmac_f32_dpp v209, v85, v141 row_shr:1 row_mask:0xf bank_mask:0xf
	v_fmac_f32_dpp v210, v86, v142 row_shr:1 row_mask:0xf bank_mask:0xf
	v_fmac_f32_dpp v211, v87, v143 row_shr:1 row_mask:0xf bank_mask:0xf
	v_fmac_f32_dpp v212, v72, v132 row_shr:1 row_mask:0xf bank_mask:0xf
	v_fmac_f32_dpp v213, v73, v133 row_shr:1 row_mask:0xf bank_mask:0xf
	v_fmac_f32_dpp v214, v74, v134 row_shr:1 row_mask:0xf bank_mask:0xf
	v_fmac_f32_dpp v215, v75, v135 row_shr:1 row_mask:0xf bank_mask:0xf
	v_fmac_f32_dpp v208, v100, v140 row_shl:15 row_mask:0xf bank_mask:0xf
	v_fmac_f32_dpp v209, v101, v141 row_shl:15 row_mask:0xf bank_mask:0xf
	v_fmac_f32_dpp v210, v102, v142 row_shl:15 row_mask:0xf bank_mask:0xf
	v_fmac_f32_dpp v211, v103, v143 row_shl:15 row_mask:0xf bank_mask:0xf
	v_fmac_f32_dpp v212, v88, v132 row_shl:15 row_mask:0xf bank_mask:0xf
	v_fmac_f32_dpp v213, v89, v133 row_shl:15 row_mask:0xf bank_mask:0xf
	v_fmac_f32_dpp v214, v90, v134 row_shl:15 row_mask:0xf bank_mask:0xf
	v_fmac_f32_dpp v215, v91, v135 row_shl:15 row_mask:0xf bank_mask:0xf
	v_fmac_f32_dpp v208, v84, v136 row_shr:2 row_mask:0xf bank_mask:0xf
	v_fmac_f32_dpp v209, v85, v137 row_shr:2 row_mask:0xf bank_mask:0xf
; DI float silu_fast(float x) { return x * __builtin_amdgcn_rcpf(1.f + __expf(-x)); }
; template <int CTRL> DI float dppf(float v) { return __builtin_bit_cast(float, __builtin_amdgcn_update_dpp(0, __builtin_bit_cast(int, v), CTRL, 0xf, 0xf, true)); }
; DI void Epi::fused(const f32x4 (&acc)[2][2][4][2], int pm, int pn, int wr, int wc, int fr, int fq) const {
;     ...
;         const int ncol = pn * 256 + bj * 128 + wc * 32 + 8 * fq, j0 = (ncol >> 3) * 4;
;         const f32x4 wa0 = *(const f32x4*)(E.cf0 + j0), wa1 = *(const f32x4*)(E.cf0 + FF2 + j0), wa2 = *(const f32x4*)(E.cf0 + 2 * FF2 + j0);
;         const f32x4 wb0 = *(const f32x4*)(E.cf0 + FFH + j0), wb1 = *(const f32x4*)(E.cf0 + FF2 + FFH + j0), wb2 = *(const f32x4*)(E.cf0 + 2 * FF2 + FFH + j0);
;         const f32x4 ba = *(const f32x4*)(E.cf1 + j0), bb = *(const f32x4*)(E.cf1 + FFH + j0);
;     ...
;                 for (int e = 0; e < 4; ++e) {
;                     const float a1 = dppf<0x111>(ca[e]) + dppf<0x10F>(pa[e]), a2 = dppf<0x112>(ca[e]) + dppf<0x10E>(pa[e]);
;                     const float b1 = dppf<0x111>(cb[e]) + dppf<0x10F>(pb[e]), b2 = dppf<0x112>(cb[e]) + dppf<0x10E>(pb[e]);
;                     const float ya = fmaf(wa0[e], a2, fmaf(wa1[e], a1, fmaf(wa2[e], ca[e], ba[e])));
;                     const float yb = fmaf(wb0[e], b2, fmaf(wb1[e], b1, fmaf(wb2[e], cb[e], bb[e])));
;                     o[e] = silu_fast(ya) * yb; }
;                 if (m > 0 || fr >= 2) { u32x2 w; w.x = pk2(o[0], o[1]); w.y = pk2(o[2], o[3]); *(u32x2*)(E.d0 + (size_t)row * FFH + j0) = w; }
;                 if ((m == 0 && fr < 2) || (m == 3 && fr >= 14)) { float* hb = E.f0 + ((size_t)(row >> 6) * 4 + (m == 0 ? fr : fr - 12)) * FF2 + ncol; *(f32x4*)hb = ca; *(f32x4*)(hb + 4) = cb; }
;                 pa = ca; pb = cb;
	v_fmac_f32_dpp v210, v86, v138 row_shr:2 row_mask:0xf bank_mask:0xf
	v_fmac_f32_dpp v211, v87, v139 row_shr:2 row_mask:0xf bank_mask:0xf
	v_fmac_f32_dpp v212, v72, v128 row_shr:2 row_mask:0xf bank_mask:0xf
	v_fmac_f32_dpp v213, v73, v129 row_shr:2 row_mask:0xf bank_mask:0xf
	v_fmac_f32_dpp v214, v74, v130 row_shr:2 row_mask:0xf bank_mask:0xf
	v_fmac_f32_dpp v215, v75, v131 row_shr:2 row_mask:0xf bank_mask:0xf
	v_fmac_f32_dpp v208, v100, v136 row_shl:14 row_mask:0xf bank_mask:0xf
	v_fmac_f32_dpp v209, v101, v137 row_shl:14 row_mask:0xf bank_mask:0xf
	v_fmac_f32_dpp v210, v102, v138 row_shl:14 row_mask:0xf bank_mask:0xf
	v_fmac_f32_dpp v211, v103, v139 row_shl:14 row_mask:0xf bank_mask:0xf
	v_fmac_f32_dpp v212, v88, v128 row_shl:14 row_mask:0xf bank_mask:0xf
	v_fmac_f32_dpp v213, v89, v129 row_shl:14 row_mask:0xf bank_mask:0xf
	v_fmac_f32_dpp v214, v90, v130 row_shl:14 row_mask:0xf bank_mask:0xf
	v_fmac_f32_dpp v215, v91, v131 row_shl:14 row_mask:0xf bank_mask:0xf
	v_mul_f32_e32 v216, 0xbfb8aa3b, v208
	v_mul_f32_e32 v217, 0xbfb8aa3b, v209
	v_mul_f32_e32 v218, 0xbfb8aa3b, v210
	v_mul_f32_e32 v219, 0xbfb8aa3b, v211
	v_exp_f32_e32 v216, v216
	v_exp_f32_e32 v217, v217
	v_exp_f32_e32 v218, v218
	v_exp_f32_e32 v219, v219
	v_add_f32_e32 v216, 1.0, v216
	v_add_f32_e32 v217, 1.0, v217
	v_add_f32_e32 v218, 1.0, v218
	v_add_f32_e32 v219, 1.0, v219
	v_rcp_f32_e32 v216, v216
	v_rcp_f32_e32 v217, v217
	v_rcp_f32_e32 v218, v218
	v_rcp_f32_e32 v219, v219
	s_mov_b32 s80, 0x42000
	s_mov_b32 s81, 0
	v_lshl_add_u64 v[222:223], v[224:225], 0, s[80:81]
	v_mul_f32_e32 v208, v208, v216
	v_mul_f32_e32 v209, v209, v217
	v_mul_f32_e32 v210, v210, v218
	v_mul_f32_e32 v211, v211, v219
	v_mul_f32_e32 v208, v212, v208
	v_mul_f32_e32 v209, v213, v209
	v_mul_f32_e32 v210, v214, v210
	v_mul_f32_e32 v211, v215, v211
	v_cvt_pk_bf16_f32 v220, v208, v209
	v_cvt_pk_bf16_f32 v221, v210, v211
	global_store_dwordx2 v[222:223], v[220:221], off
	s_ashr_i32 s80, s71, 6
	s_lshl_b32 s80, s80, 2
	v_add_u32_e32 v226, s80, v190
	v_mov_b64_e32 v[222:223], s[8:9]
	s_movk_i32 s80, 0x5800
	v_mad_i64_i32 v[222:223], s[78:79], v226, s80, v[222:223]
	v_lshl_add_u64 v[222:223], v[228:229], 2, v[222:223]
	s_and_saveexec_b64 s[76:77], s[42:43]
	global_store_dwordx4 v[222:223], v[84:87], off
	global_store_dwordx4 v[222:223], v[72:75], off offset:16
	s_or_b64 exec, exec, s[76:77]
	v_add_u32_e32 v238, 0x80, v240
	v_lshlrev_b32_e32 v238, 1, v238
	v_mov_b32_e32 v239, 0
	v_lshl_add_u64 v[84:85], s[22:23], 0, v[238:239]
	global_load_dwordx4 v[84:87], v[84:85], off
	v_readlane_b32 s76, v254, 54
	v_readlane_b32 s77, v254, 55
	s_nop 1
	v_lshl_add_u64 v[88:89], s[76:77], 0, v[238:239]
	global_load_dwordx4 v[88:91], v[88:89], off
	v_readlane_b32 s76, v254, 56
	v_readlane_b32 s77, v254, 57
	s_nop 1
	v_lshl_add_u64 v[100:101], s[76:77], 0, v[238:239]
	global_load_dwordx4 v[100:103], v[100:101], off
	v_readlane_b32 s76, v255, 4
	v_readlane_b32 s77, v255, 5
	s_nop 1
	v_lshl_add_u64 v[104:105], s[76:77], 0, v[238:239]
	global_load_dwordx4 v[104:107], v[104:105], off
	v_readlane_b32 s76, v255, 6
	v_readlane_b32 s77, v255, 7
	s_nop 1
	v_lshl_add_u64 v[116:117], s[76:77], 0, v[238:239]
	global_load_dwordx4 v[116:119], v[116:117], off
	v_readlane_b32 s76, v255, 8
	v_readlane_b32 s77, v255, 9
	s_nop 1
	v_lshl_add_u64 v[120:121], s[76:77], 0, v[238:239]
	global_load_dwordx4 v[120:123], v[120:121], off
	v_readlane_b32 s76, v254, 49
	v_readlane_b32 s77, v254, 50
	s_nop 1
	v_lshl_add_u64 v[124:125], s[76:77], 0, v[238:239]
	global_load_dwordx4 v[124:127], v[124:125], off
	v_lshl_add_u64 v[72:73], s[72:73], 0, v[238:239]
	global_load_dwordx4 v[72:75], v[72:73], off
	v_add_u32_e32 v228, 128, v199
	v_mov_b64_e32 v[224:225], s[12:13]
	s_movk_i32 s80, 0x1600
	v_mad_i64_i32 v[224:225], s[78:79], v228, s80, v[224:225]
	v_mov_b32_e32 v228, v240
	v_mov_b32_e32 v229, 0
	v_lshl_add_u64 v[224:225], v[228:229], 0, v[224:225]
	v_fma_f32 v160, v152, v60, v156
	v_fma_f32 v161, v153, v61, v157
	v_fma_f32 v162, v154, v62, v158
	v_fma_f32 v163, v155, v63, v159
	v_fma_f32 v164, v144, v56, v148
	v_fma_f32 v165, v145, v57, v149
	v_fma_f32 v166, v146, v58, v150
	v_fma_f32 v167, v147, v59, v151
	v_fmac_f32_dpp v160, v60, v140 row_shr:1 row_mask:0xf bank_mask:0xf
	v_fmac_f32_dpp v161, v61, v141 row_shr:1 row_mask:0xf bank_mask:0xf
	v_fmac_f32_dpp v162, v62, v142 row_shr:1 row_mask:0xf bank_mask:0xf
	v_fmac_f32_dpp v163, v63, v143 row_shr:1 row_mask:0xf bank_mask:0xf
	v_fmac_f32_dpp v164, v56, v132 row_shr:1 row_mask:0xf bank_mask:0xf
	v_fmac_f32_dpp v165, v57, v133 row_shr:1 row_mask:0xf bank_mask:0xf
	v_fmac_f32_dpp v166, v58, v134 row_shr:1 row_mask:0xf bank_mask:0xf
	v_fmac_f32_dpp v167, v59, v135 row_shr:1 row_mask:0xf bank_mask:0xf
	v_fmac_f32_dpp v160, v60, v136 row_shr:2 row_mask:0xf bank_mask:0xf
	v_fmac_f32_dpp v161, v61, v137 row_shr:2 row_mask:0xf bank_mask:0xf
	v_fmac_f32_dpp v162, v62, v138 row_shr:2 row_mask:0xf bank_mask:0xf
	v_fmac_f32_dpp v163, v63, v139 row_shr:2 row_mask:0xf bank_mask:0xf
	v_fmac_f32_dpp v164, v56, v128 row_shr:2 row_mask:0xf bank_mask:0xf
	v_fmac_f32_dpp v165, v57, v129 row_shr:2 row_mask:0xf bank_mask:0xf
	v_fmac_f32_dpp v166, v58, v130 row_shr:2 row_mask:0xf bank_mask:0xf
	v_fmac_f32_dpp v167, v59, v131 row_shr:2 row_mask:0xf bank_mask:0xf
	v_mul_f32_e32 v168, 0xbfb8aa3b, v160
	v_mul_f32_e32 v169, 0xbfb8aa3b, v161
	v_mul_f32_e32 v170, 0xbfb8aa3b, v162
	v_mul_f32_e32 v171, 0xbfb8aa3b, v163
	v_exp_f32_e32 v168, v168
	v_exp_f32_e32 v169, v169
	v_exp_f32_e32 v170, v170
	v_exp_f32_e32 v171, v171
	v_add_f32_e32 v168, 1.0, v168
	v_add_f32_e32 v169, 1.0, v169
	v_add_f32_e32 v170, 1.0, v170
	v_add_f32_e32 v171, 1.0, v171
; DI float silu_fast(float x) { return x * __builtin_amdgcn_rcpf(1.f + __expf(-x)); }
; template <int CTRL> DI float dppf(float v) { return __builtin_bit_cast(float, __builtin_amdgcn_update_dpp(0, __builtin_bit_cast(int, v), CTRL, 0xf, 0xf, true)); }
; DI void Epi::fused(const f32x4 (&acc)[2][2][4][2], int pm, int pn, int wr, int wc, int fr, int fq) const {
;     ...
;                 for (int e = 0; e < 4; ++e) {
;                     const float a1 = dppf<0x111>(ca[e]) + dppf<0x10F>(pa[e]), a2 = dppf<0x112>(ca[e]) + dppf<0x10E>(pa[e]);
;                     const float b1 = dppf<0x111>(cb[e]) + dppf<0x10F>(pb[e]), b2 = dppf<0x112>(cb[e]) + dppf<0x10E>(pb[e]);
;                     const float ya = fmaf(wa0[e], a2, fmaf(wa1[e], a1, fmaf(wa2[e], ca[e], ba[e])));
;                     const float yb = fmaf(wb0[e], b2, fmaf(wb1[e], b1, fmaf(wb2[e], cb[e], bb[e])));
;                     o[e] = silu_fast(ya) * yb; }
;                 if (m > 0 || fr >= 2) { u32x2 w; w.x = pk2(o[0], o[1]); w.y = pk2(o[2], o[3]); *(u32x2*)(E.d0 + (size_t)row * FFH + j0) = w; }
;                 if ((m == 0 && fr < 2) || (m == 3 && fr >= 14)) { float* hb = E.f0 + ((size_t)(row >> 6) * 4 + (m == 0 ? fr : fr - 12)) * FF2 + ncol; *(f32x4*)hb = ca; *(f32x4*)(hb + 4) = cb; }
;                 pa = ca; pb = cb;
	v_rcp_f32_e32 v168, v168
	v_rcp_f32_e32 v169, v169
	v_rcp_f32_e32 v170, v170
	v_rcp_f32_e32 v171, v171
	v_mov_b64_e32 v[174:175], v[224:225]
	v_mul_f32_e32 v160, v160, v168
	v_mul_f32_e32 v161, v161, v169
	v_mul_f32_e32 v162, v162, v170
	v_mul_f32_e32 v163, v163, v171
	v_mul_f32_e32 v160, v164, v160
	v_mul_f32_e32 v161, v165, v161
	v_mul_f32_e32 v162, v166, v162
	v_mul_f32_e32 v163, v167, v163
	v_cvt_pk_bf16_f32 v172, v160, v161
	v_cvt_pk_bf16_f32 v173, v162, v163
	s_and_saveexec_b64 s[76:77], s[38:39]
	global_store_dwordx2 v[174:175], v[172:173], off
	s_or_b64 exec, exec, s[76:77]
	s_ashr_i32 s80, s71, 6
	s_lshl_b32 s80, s80, 2
	s_add_i32 s80, s80, 8
	v_add_u32_e32 v226, s80, v188
	v_mov_b64_e32 v[174:175], s[8:9]
	s_movk_i32 s80, 0x5800
	v_mad_i64_i32 v[174:175], s[78:79], v226, s80, v[174:175]
	v_lshl_add_u64 v[174:175], v[228:229], 2, v[174:175]
	s_and_saveexec_b64 s[76:77], s[40:41]
	global_store_dwordx4 v[174:175], v[60:63], off
	global_store_dwordx4 v[174:175], v[56:59], off offset:16
	s_or_b64 exec, exec, s[76:77]
	v_fma_f32 v208, v152, v52, v156
	v_fma_f32 v209, v153, v53, v157
	v_fma_f32 v210, v154, v54, v158
	v_fma_f32 v211, v155, v55, v159
	v_fma_f32 v212, v144, v40, v148
	v_fma_f32 v213, v145, v41, v149
	v_fma_f32 v214, v146, v42, v150
	v_fma_f32 v215, v147, v43, v151
	v_fmac_f32_dpp v208, v52, v140 row_shr:1 row_mask:0xf bank_mask:0xf
	v_fmac_f32_dpp v209, v53, v141 row_shr:1 row_mask:0xf bank_mask:0xf
	v_fmac_f32_dpp v210, v54, v142 row_shr:1 row_mask:0xf bank_mask:0xf
	v_fmac_f32_dpp v211, v55, v143 row_shr:1 row_mask:0xf bank_mask:0xf
	v_fmac_f32_dpp v212, v40, v132 row_shr:1 row_mask:0xf bank_mask:0xf
	v_fmac_f32_dpp v213, v41, v133 row_shr:1 row_mask:0xf bank_mask:0xf
	v_fmac_f32_dpp v214, v42, v134 row_shr:1 row_mask:0xf bank_mask:0xf
	v_fmac_f32_dpp v215, v43, v135 row_shr:1 row_mask:0xf bank_mask:0xf
	v_fmac_f32_dpp v208, v60, v140 row_shl:15 row_mask:0xf bank_mask:0xf
	v_fmac_f32_dpp v209, v61, v141 row_shl:15 row_mask:0xf bank_mask:0xf
	v_fmac_f32_dpp v210, v62, v142 row_shl:15 row_mask:0xf bank_mask:0xf
	v_fmac_f32_dpp v211, v63, v143 row_shl:15 row_mask:0xf bank_mask:0xf
	v_fmac_f32_dpp v212, v56, v132 row_shl:15 row_mask:0xf bank_mask:0xf
	v_fmac_f32_dpp v213, v57, v133 row_shl:15 row_mask:0xf bank_mask:0xf
	v_fmac_f32_dpp v214, v58, v134 row_shl:15 row_mask:0xf bank_mask:0xf
	v_fmac_f32_dpp v215, v59, v135 row_shl:15 row_mask:0xf bank_mask:0xf
	v_fmac_f32_dpp v208, v52, v136 row_shr:2 row_mask:0xf bank_mask:0xf
	v_fmac_f32_dpp v209, v53, v137 row_shr:2 row_mask:0xf bank_mask:0xf
	v_fmac_f32_dpp v210, v54, v138 row_shr:2 row_mask:0xf bank_mask:0xf
	v_fmac_f32_dpp v211, v55, v139 row_shr:2 row_mask:0xf bank_mask:0xf
	v_fmac_f32_dpp v212, v40, v128 row_shr:2 row_mask:0xf bank_mask:0xf
	v_fmac_f32_dpp v213, v41, v129 row_shr:2 row_mask:0xf bank_mask:0xf
	v_fmac_f32_dpp v214, v42, v130 row_shr:2 row_mask:0xf bank_mask:0xf
	v_fmac_f32_dpp v215, v43, v131 row_shr:2 row_mask:0xf bank_mask:0xf
	v_fmac_f32_dpp v208, v60, v136 row_shl:14 row_mask:0xf bank_mask:0xf
	v_fmac_f32_dpp v209, v61, v137 row_shl:14 row_mask:0xf bank_mask:0xf
	v_fmac_f32_dpp v210, v62, v138 row_shl:14 row_mask:0xf bank_mask:0xf
	v_fmac_f32_dpp v211, v63, v139 row_shl:14 row_mask:0xf bank_mask:0xf
	v_fmac_f32_dpp v212, v56, v128 row_shl:14 row_mask:0xf bank_mask:0xf
	v_fmac_f32_dpp v213, v57, v129 row_shl:14 row_mask:0xf bank_mask:0xf
	v_fmac_f32_dpp v214, v58, v130 row_shl:14 row_mask:0xf bank_mask:0xf
	v_fmac_f32_dpp v215, v59, v131 row_shl:14 row_mask:0xf bank_mask:0xf
	v_mul_f32_e32 v216, 0xbfb8aa3b, v208
	v_mul_f32_e32 v217, 0xbfb8aa3b, v209
	v_mul_f32_e32 v218, 0xbfb8aa3b, v210
	v_mul_f32_e32 v219, 0xbfb8aa3b, v211
	v_exp_f32_e32 v216, v216
	v_exp_f32_e32 v217, v217
	v_exp_f32_e32 v218, v218
	v_exp_f32_e32 v219, v219
	v_add_f32_e32 v216, 1.0, v216
	v_add_f32_e32 v217, 1.0, v217
	v_add_f32_e32 v218, 1.0, v218
	v_add_f32_e32 v219, 1.0, v219
	v_rcp_f32_e32 v216, v216
	v_rcp_f32_e32 v217, v217
	v_rcp_f32_e32 v218, v218
	v_rcp_f32_e32 v219, v219
	s_mov_b32 s80, 0x16000
	s_mov_b32 s81, 0
	v_lshl_add_u64 v[222:223], v[224:225], 0, s[80:81]
	v_mul_f32_e32 v208, v208, v216
	v_mul_f32_e32 v209, v209, v217
	v_mul_f32_e32 v210, v210, v218
	v_mul_f32_e32 v211, v211, v219
	v_mul_f32_e32 v208, v212, v208
	v_mul_f32_e32 v209, v213, v209
	v_mul_f32_e32 v210, v214, v210
	v_mul_f32_e32 v211, v215, v211
	v_cvt_pk_bf16_f32 v220, v208, v209
	v_cvt_pk_bf16_f32 v221, v210, v211
	global_store_dwordx2 v[222:223], v[220:221], off
	v_fma_f32 v160, v152, v36, v156
	v_fma_f32 v161, v153, v37, v157
	v_fma_f32 v162, v154, v38, v158
	v_fma_f32 v163, v155, v39, v159
	v_fma_f32 v164, v144, v16, v148
	v_fma_f32 v165, v145, v17, v149
	v_fma_f32 v166, v146, v18, v150
	v_fma_f32 v167, v147, v19, v151
	v_fmac_f32_dpp v160, v36, v140 row_shr:1 row_mask:0xf bank_mask:0xf
	v_fmac_f32_dpp v161, v37, v141 row_shr:1 row_mask:0xf bank_mask:0xf
	v_fmac_f32_dpp v162, v38, v142 row_shr:1 row_mask:0xf bank_mask:0xf
	v_fmac_f32_dpp v163, v39, v143 row_shr:1 row_mask:0xf bank_mask:0xf
	v_fmac_f32_dpp v164, v16, v132 row_shr:1 row_mask:0xf bank_mask:0xf
	v_fmac_f32_dpp v165, v17, v133 row_shr:1 row_mask:0xf bank_mask:0xf
	v_fmac_f32_dpp v166, v18, v134 row_shr:1 row_mask:0xf bank_mask:0xf
	v_fmac_f32_dpp v167, v19, v135 row_shr:1 row_mask:0xf bank_mask:0xf
	v_fmac_f32_dpp v160, v52, v140 row_shl:15 row_mask:0xf bank_mask:0xf
	v_fmac_f32_dpp v161, v53, v141 row_shl:15 row_mask:0xf bank_mask:0xf
	v_fmac_f32_dpp v162, v54, v142 row_shl:15 row_mask:0xf bank_mask:0xf
	v_fmac_f32_dpp v163, v55, v143 row_shl:15 row_mask:0xf bank_mask:0xf
	v_fmac_f32_dpp v164, v40, v132 row_shl:15 row_mask:0xf bank_mask:0xf
; DI float silu_fast(float x) { return x * __builtin_amdgcn_rcpf(1.f + __expf(-x)); }
; template <int CTRL> DI float dppf(float v) { return __builtin_bit_cast(float, __builtin_amdgcn_update_dpp(0, __builtin_bit_cast(int, v), CTRL, 0xf, 0xf, true)); }
; DI void Epi::fused(const f32x4 (&acc)[2][2][4][2], int pm, int pn, int wr, int wc, int fr, int fq) const {
;     ...
;             for (int m = 0; m < 4; ++m) {
;                 const f32x4 ca = acc[ai][bj][m][0], cb = acc[ai][bj][m][1];
;                 const int row = pm * 256 + ai * 128 + wr * 64 + m * 16 + fr;
;                 float o[4];
; #pragma unroll
;                 for (int e = 0; e < 4; ++e) {
;                     const float a1 = dppf<0x111>(ca[e]) + dppf<0x10F>(pa[e]), a2 = dppf<0x112>(ca[e]) + dppf<0x10E>(pa[e]);
;                     const float b1 = dppf<0x111>(cb[e]) + dppf<0x10F>(pb[e]), b2 = dppf<0x112>(cb[e]) + dppf<0x10E>(pb[e]);
;                     const float ya = fmaf(wa0[e], a2, fmaf(wa1[e], a1, fmaf(wa2[e], ca[e], ba[e])));
;                     const float yb = fmaf(wb0[e], b2, fmaf(wb1[e], b1, fmaf(wb2[e], cb[e], bb[e])));
;                     o[e] = silu_fast(ya) * yb; }
;                 if (m > 0 || fr >= 2) { u32x2 w; w.x = pk2(o[0], o[1]); w.y = pk2(o[2], o[3]); *(u32x2*)(E.d0 + (size_t)row * FFH + j0) = w; }
;                 if ((m == 0 && fr < 2) || (m == 3 && fr >= 14)) { float* hb = E.f0 + ((size_t)(row >> 6) * 4 + (m == 0 ? fr : fr - 12)) * FF2 + ncol; *(f32x4*)hb = ca; *(f32x4*)(hb + 4) = cb; }
;                 pa = ca; pb = cb;
	v_fmac_f32_dpp v165, v41, v133 row_shl:15 row_mask:0xf bank_mask:0xf
	v_fmac_f32_dpp v166, v42, v134 row_shl:15 row_mask:0xf bank_mask:0xf
	v_fmac_f32_dpp v167, v43, v135 row_shl:15 row_mask:0xf bank_mask:0xf
	v_fmac_f32_dpp v160, v36, v136 row_shr:2 row_mask:0xf bank_mask:0xf
	v_fmac_f32_dpp v161, v37, v137 row_shr:2 row_mask:0xf bank_mask:0xf
	v_fmac_f32_dpp v162, v38, v138 row_shr:2 row_mask:0xf bank_mask:0xf
	v_fmac_f32_dpp v163, v39, v139 row_shr:2 row_mask:0xf bank_mask:0xf
	v_fmac_f32_dpp v164, v16, v128 row_shr:2 row_mask:0xf bank_mask:0xf
	v_fmac_f32_dpp v165, v17, v129 row_shr:2 row_mask:0xf bank_mask:0xf
	v_fmac_f32_dpp v166, v18, v130 row_shr:2 row_mask:0xf bank_mask:0xf
	v_fmac_f32_dpp v167, v19, v131 row_shr:2 row_mask:0xf bank_mask:0xf
	v_fmac_f32_dpp v160, v52, v136 row_shl:14 row_mask:0xf bank_mask:0xf
	v_fmac_f32_dpp v161, v53, v137 row_shl:14 row_mask:0xf bank_mask:0xf
	v_fmac_f32_dpp v162, v54, v138 row_shl:14 row_mask:0xf bank_mask:0xf
	v_fmac_f32_dpp v163, v55, v139 row_shl:14 row_mask:0xf bank_mask:0xf
	v_fmac_f32_dpp v164, v40, v128 row_shl:14 row_mask:0xf bank_mask:0xf
	v_fmac_f32_dpp v165, v41, v129 row_shl:14 row_mask:0xf bank_mask:0xf
	v_fmac_f32_dpp v166, v42, v130 row_shl:14 row_mask:0xf bank_mask:0xf
	v_fmac_f32_dpp v167, v43, v131 row_shl:14 row_mask:0xf bank_mask:0xf
	v_mul_f32_e32 v168, 0xbfb8aa3b, v160
	v_mul_f32_e32 v169, 0xbfb8aa3b, v161
	v_mul_f32_e32 v170, 0xbfb8aa3b, v162
	v_mul_f32_e32 v171, 0xbfb8aa3b, v163
	v_exp_f32_e32 v168, v168
	v_exp_f32_e32 v169, v169
	v_exp_f32_e32 v170, v170
	v_exp_f32_e32 v171, v171
	v_add_f32_e32 v168, 1.0, v168
	v_add_f32_e32 v169, 1.0, v169
	v_add_f32_e32 v170, 1.0, v170
	v_add_f32_e32 v171, 1.0, v171
	v_rcp_f32_e32 v168, v168
	v_rcp_f32_e32 v169, v169
	v_rcp_f32_e32 v170, v170
	v_rcp_f32_e32 v171, v171
	s_mov_b32 s80, 0x2c000
	s_mov_b32 s81, 0
	v_lshl_add_u64 v[174:175], v[224:225], 0, s[80:81]
	v_mul_f32_e32 v160, v160, v168
	v_mul_f32_e32 v161, v161, v169
	v_mul_f32_e32 v162, v162, v170
	v_mul_f32_e32 v163, v163, v171
	v_mul_f32_e32 v160, v164, v160
	v_mul_f32_e32 v161, v165, v161
	v_mul_f32_e32 v162, v166, v162
	v_mul_f32_e32 v163, v167, v163
	v_cvt_pk_bf16_f32 v172, v160, v161
	v_cvt_pk_bf16_f32 v173, v162, v163
	global_store_dwordx2 v[174:175], v[172:173], off
	v_fma_f32 v208, v152, v12, v156
	v_fma_f32 v209, v153, v13, v157
	v_fma_f32 v210, v154, v14, v158
	v_fma_f32 v211, v155, v15, v159
	v_fma_f32 v212, v144, v0, v148
	v_fma_f32 v213, v145, v1, v149
	v_fma_f32 v214, v146, v2, v150
	v_fma_f32 v215, v147, v3, v151
	v_fmac_f32_dpp v208, v12, v140 row_shr:1 row_mask:0xf bank_mask:0xf
	v_fmac_f32_dpp v209, v13, v141 row_shr:1 row_mask:0xf bank_mask:0xf
	v_fmac_f32_dpp v210, v14, v142 row_shr:1 row_mask:0xf bank_mask:0xf
	v_fmac_f32_dpp v211, v15, v143 row_shr:1 row_mask:0xf bank_mask:0xf
	v_fmac_f32_dpp v212, v0, v132 row_shr:1 row_mask:0xf bank_mask:0xf
	v_fmac_f32_dpp v213, v1, v133 row_shr:1 row_mask:0xf bank_mask:0xf
	v_fmac_f32_dpp v214, v2, v134 row_shr:1 row_mask:0xf bank_mask:0xf
	v_fmac_f32_dpp v215, v3, v135 row_shr:1 row_mask:0xf bank_mask:0xf
	v_fmac_f32_dpp v208, v36, v140 row_shl:15 row_mask:0xf bank_mask:0xf
	v_fmac_f32_dpp v209, v37, v141 row_shl:15 row_mask:0xf bank_mask:0xf
	v_fmac_f32_dpp v210, v38, v142 row_shl:15 row_mask:0xf bank_mask:0xf
	v_fmac_f32_dpp v211, v39, v143 row_shl:15 row_mask:0xf bank_mask:0xf
	v_fmac_f32_dpp v212, v16, v132 row_shl:15 row_mask:0xf bank_mask:0xf
	v_fmac_f32_dpp v213, v17, v133 row_shl:15 row_mask:0xf bank_mask:0xf
	v_fmac_f32_dpp v214, v18, v134 row_shl:15 row_mask:0xf bank_mask:0xf
	v_fmac_f32_dpp v215, v19, v135 row_shl:15 row_mask:0xf bank_mask:0xf
	v_fmac_f32_dpp v208, v12, v136 row_shr:2 row_mask:0xf bank_mask:0xf
	v_fmac_f32_dpp v209, v13, v137 row_shr:2 row_mask:0xf bank_mask:0xf
	v_fmac_f32_dpp v210, v14, v138 row_shr:2 row_mask:0xf bank_mask:0xf
	v_fmac_f32_dpp v211, v15, v139 row_shr:2 row_mask:0xf bank_mask:0xf
	v_fmac_f32_dpp v212, v0, v128 row_shr:2 row_mask:0xf bank_mask:0xf
	v_fmac_f32_dpp v213, v1, v129 row_shr:2 row_mask:0xf bank_mask:0xf
	v_fmac_f32_dpp v214, v2, v130 row_shr:2 row_mask:0xf bank_mask:0xf
	v_fmac_f32_dpp v215, v3, v131 row_shr:2 row_mask:0xf bank_mask:0xf
	v_fmac_f32_dpp v208, v36, v136 row_shl:14 row_mask:0xf bank_mask:0xf
	v_fmac_f32_dpp v209, v37, v137 row_shl:14 row_mask:0xf bank_mask:0xf
	v_fmac_f32_dpp v210, v38, v138 row_shl:14 row_mask:0xf bank_mask:0xf
	v_fmac_f32_dpp v211, v39, v139 row_shl:14 row_mask:0xf bank_mask:0xf
	v_fmac_f32_dpp v212, v16, v128 row_shl:14 row_mask:0xf bank_mask:0xf
	v_fmac_f32_dpp v213, v17, v129 row_shl:14 row_mask:0xf bank_mask:0xf
	v_fmac_f32_dpp v214, v18, v130 row_shl:14 row_mask:0xf bank_mask:0xf
	v_fmac_f32_dpp v215, v19, v131 row_shl:14 row_mask:0xf bank_mask:0xf
	v_mul_f32_e32 v216, 0xbfb8aa3b, v208
	v_mul_f32_e32 v217, 0xbfb8aa3b, v209
	v_mul_f32_e32 v218, 0xbfb8aa3b, v210
	v_mul_f32_e32 v219, 0xbfb8aa3b, v211
	v_exp_f32_e32 v216, v216
	v_exp_f32_e32 v217, v217
	v_exp_f32_e32 v218, v218
	v_exp_f32_e32 v219, v219
	v_add_f32_e32 v216, 1.0, v216
	v_add_f32_e32 v217, 1.0, v217
	v_add_f32_e32 v218, 1.0, v218
	v_add_f32_e32 v219, 1.0, v219
	v_rcp_f32_e32 v216, v216
	v_rcp_f32_e32 v217, v217
	v_rcp_f32_e32 v218, v218
	v_rcp_f32_e32 v219, v219
	s_mov_b32 s80, 0x42000
	s_mov_b32 s81, 0
	v_lshl_add_u64 v[222:223], v[224:225], 0, s[80:81]
	v_mul_f32_e32 v208, v208, v216
	v_mul_f32_e32 v209, v209, v217
	v_mul_f32_e32 v210, v210, v218
	v_mul_f32_e32 v211, v211, v219
	v_mul_f32_e32 v208, v212, v208
	v_mul_f32_e32 v209, v213, v209
	v_mul_f32_e32 v210, v214, v210
	v_mul_f32_e32 v211, v215, v211
	v_cvt_pk_bf16_f32 v220, v208, v209
	v_cvt_pk_bf16_f32 v221, v210, v211
	global_store_dwordx2 v[222:223], v[220:221], off
	s_ashr_i32 s80, s71, 6
	s_lshl_b32 s80, s80, 2
	s_add_i32 s80, s80, 8
	v_add_u32_e32 v226, s80, v190
	v_mov_b64_e32 v[222:223], s[8:9]
	s_movk_i32 s80, 0x5800
	v_mad_i64_i32 v[222:223], s[78:79], v226, s80, v[222:223]
	v_lshl_add_u64 v[222:223], v[228:229], 2, v[222:223]
	s_and_saveexec_b64 s[76:77], s[42:43]
	global_store_dwordx4 v[222:223], v[12:15], off
	global_store_dwordx4 v[222:223], v[0:3], off offset:16
	s_or_b64 exec, exec, s[76:77]
	v_mov_b32_e32 v228, v199
	v_mov_b64_e32 v[224:225], s[12:13]
	s_movk_i32 s80, 0x1600
	v_mad_i64_i32 v[224:225], s[78:79], v228, s80, v[224:225]
	v_add_u32_e32 v228, 128, v240
	v_mov_b32_e32 v229, 0
	v_lshl_add_u64 v[224:225], v[228:229], 0, v[224:225]
	s_waitcnt vmcnt(8)
; DI float silu_fast(float x) { return x * __builtin_amdgcn_rcpf(1.f + __expf(-x)); }
; template <int CTRL> DI float dppf(float v) { return __builtin_bit_cast(float, __builtin_amdgcn_update_dpp(0, __builtin_bit_cast(int, v), CTRL, 0xf, 0xf, true)); }
; DI void Epi::fused(const f32x4 (&acc)[2][2][4][2], int pm, int pn, int wr, int wc, int fr, int fq) const {
;     ...
;             for (int m = 0; m < 4; ++m) {
;                 const f32x4 ca = acc[ai][bj][m][0], cb = acc[ai][bj][m][1];
;                 const int row = pm * 256 + ai * 128 + wr * 64 + m * 16 + fr;
;                 float o[4];
; #pragma unroll
;                 for (int e = 0; e < 4; ++e) {
;                     const float a1 = dppf<0x111>(ca[e]) + dppf<0x10F>(pa[e]), a2 = dppf<0x112>(ca[e]) + dppf<0x10E>(pa[e]);
;                     const float b1 = dppf<0x111>(cb[e]) + dppf<0x10F>(pb[e]), b2 = dppf<0x112>(cb[e]) + dppf<0x10E>(pb[e]);
;                     const float ya = fmaf(wa0[e], a2, fmaf(wa1[e], a1, fmaf(wa2[e], ca[e], ba[e])));
;                     const float yb = fmaf(wb0[e], b2, fmaf(wb1[e], b1, fmaf(wb2[e], cb[e], bb[e])));
;                     o[e] = silu_fast(ya) * yb; }
;                 if (m > 0 || fr >= 2) { u32x2 w; w.x = pk2(o[0], o[1]); w.y = pk2(o[2], o[3]); *(u32x2*)(E.d0 + (size_t)row * FFH + j0) = w; }
;                 if ((m == 0 && fr < 2) || (m == 3 && fr >= 14)) { float* hb = E.f0 + ((size_t)(row >> 6) * 4 + (m == 0 ? fr : fr - 12)) * FF2 + ncol; *(f32x4*)hb = ca; *(f32x4*)(hb + 4) = cb; }
;                 pa = ca; pb = cb;
	v_fma_f32 v160, v100, v112, v124
	v_fma_f32 v161, v101, v113, v125
	v_fma_f32 v162, v102, v114, v126
	v_fma_f32 v163, v103, v115, v127
	v_fma_f32 v164, v120, v108, v72
	v_fma_f32 v165, v121, v109, v73
	v_fma_f32 v166, v122, v110, v74
	v_fma_f32 v167, v123, v111, v75
	v_fmac_f32_dpp v160, v112, v88 row_shr:1 row_mask:0xf bank_mask:0xf
	v_fmac_f32_dpp v161, v113, v89 row_shr:1 row_mask:0xf bank_mask:0xf
	v_fmac_f32_dpp v162, v114, v90 row_shr:1 row_mask:0xf bank_mask:0xf
	v_fmac_f32_dpp v163, v115, v91 row_shr:1 row_mask:0xf bank_mask:0xf
	v_fmac_f32_dpp v164, v108, v116 row_shr:1 row_mask:0xf bank_mask:0xf
	v_fmac_f32_dpp v165, v109, v117 row_shr:1 row_mask:0xf bank_mask:0xf
	v_fmac_f32_dpp v166, v110, v118 row_shr:1 row_mask:0xf bank_mask:0xf
	v_fmac_f32_dpp v167, v111, v119 row_shr:1 row_mask:0xf bank_mask:0xf
	v_fmac_f32_dpp v160, v112, v84 row_shr:2 row_mask:0xf bank_mask:0xf
	v_fmac_f32_dpp v161, v113, v85 row_shr:2 row_mask:0xf bank_mask:0xf
	v_fmac_f32_dpp v162, v114, v86 row_shr:2 row_mask:0xf bank_mask:0xf
	v_fmac_f32_dpp v163, v115, v87 row_shr:2 row_mask:0xf bank_mask:0xf
	v_fmac_f32_dpp v164, v108, v104 row_shr:2 row_mask:0xf bank_mask:0xf
	v_fmac_f32_dpp v165, v109, v105 row_shr:2 row_mask:0xf bank_mask:0xf
	v_fmac_f32_dpp v166, v110, v106 row_shr:2 row_mask:0xf bank_mask:0xf
	v_fmac_f32_dpp v167, v111, v107 row_shr:2 row_mask:0xf bank_mask:0xf
	v_mul_f32_e32 v168, 0xbfb8aa3b, v160
	v_mul_f32_e32 v169, 0xbfb8aa3b, v161
	v_mul_f32_e32 v170, 0xbfb8aa3b, v162
	v_mul_f32_e32 v171, 0xbfb8aa3b, v163
	v_exp_f32_e32 v168, v168
	v_exp_f32_e32 v169, v169
	v_exp_f32_e32 v170, v170
	v_exp_f32_e32 v171, v171
	v_add_f32_e32 v168, 1.0, v168
	v_add_f32_e32 v169, 1.0, v169
	v_add_f32_e32 v170, 1.0, v170
	v_add_f32_e32 v171, 1.0, v171
	v_rcp_f32_e32 v168, v168
	v_rcp_f32_e32 v169, v169
	v_rcp_f32_e32 v170, v170
	v_rcp_f32_e32 v171, v171
	v_mov_b64_e32 v[174:175], v[224:225]
	v_mul_f32_e32 v160, v160, v168
	v_mul_f32_e32 v161, v161, v169
	v_mul_f32_e32 v162, v162, v170
	v_mul_f32_e32 v163, v163, v171
	v_mul_f32_e32 v160, v164, v160
	v_mul_f32_e32 v161, v165, v161
	v_mul_f32_e32 v162, v166, v162
	v_mul_f32_e32 v163, v167, v163
	v_cvt_pk_bf16_f32 v172, v160, v161
	v_cvt_pk_bf16_f32 v173, v162, v163
	s_and_saveexec_b64 s[76:77], s[38:39]
	global_store_dwordx2 v[174:175], v[172:173], off
	s_or_b64 exec, exec, s[76:77]
	s_ashr_i32 s80, s71, 6
	s_lshl_b32 s80, s80, 2
	v_add_u32_e32 v226, s80, v188
	v_mov_b64_e32 v[174:175], s[8:9]
	s_movk_i32 s80, 0x5800
	v_mad_i64_i32 v[174:175], s[78:79], v226, s80, v[174:175]
	v_lshl_add_u64 v[174:175], v[228:229], 2, v[174:175]
	s_and_saveexec_b64 s[76:77], s[40:41]
	global_store_dwordx4 v[174:175], v[112:115], off
	global_store_dwordx4 v[174:175], v[108:111], off offset:16
	s_or_b64 exec, exec, s[76:77]
	v_fma_f32 v208, v100, v96, v124
	v_fma_f32 v209, v101, v97, v125
	v_fma_f32 v210, v102, v98, v126
	v_fma_f32 v211, v103, v99, v127
	v_fma_f32 v212, v120, v92, v72
	v_fma_f32 v213, v121, v93, v73
	v_fma_f32 v214, v122, v94, v74
	v_fma_f32 v215, v123, v95, v75
	v_fmac_f32_dpp v208, v96, v88 row_shr:1 row_mask:0xf bank_mask:0xf
	v_fmac_f32_dpp v209, v97, v89 row_shr:1 row_mask:0xf bank_mask:0xf
	v_fmac_f32_dpp v210, v98, v90 row_shr:1 row_mask:0xf bank_mask:0xf
	v_fmac_f32_dpp v211, v99, v91 row_shr:1 row_mask:0xf bank_mask:0xf
	v_fmac_f32_dpp v212, v92, v116 row_shr:1 row_mask:0xf bank_mask:0xf
	v_fmac_f32_dpp v213, v93, v117 row_shr:1 row_mask:0xf bank_mask:0xf
	v_fmac_f32_dpp v214, v94, v118 row_shr:1 row_mask:0xf bank_mask:0xf
	v_fmac_f32_dpp v215, v95, v119 row_shr:1 row_mask:0xf bank_mask:0xf
	v_fmac_f32_dpp v208, v112, v88 row_shl:15 row_mask:0xf bank_mask:0xf
	v_fmac_f32_dpp v209, v113, v89 row_shl:15 row_mask:0xf bank_mask:0xf
	v_fmac_f32_dpp v210, v114, v90 row_shl:15 row_mask:0xf bank_mask:0xf
	v_fmac_f32_dpp v211, v115, v91 row_shl:15 row_mask:0xf bank_mask:0xf
	v_fmac_f32_dpp v212, v108, v116 row_shl:15 row_mask:0xf bank_mask:0xf
	v_fmac_f32_dpp v213, v109, v117 row_shl:15 row_mask:0xf bank_mask:0xf
	v_fmac_f32_dpp v214, v110, v118 row_shl:15 row_mask:0xf bank_mask:0xf
	v_fmac_f32_dpp v215, v111, v119 row_shl:15 row_mask:0xf bank_mask:0xf
	v_fmac_f32_dpp v208, v96, v84 row_shr:2 row_mask:0xf bank_mask:0xf
	v_fmac_f32_dpp v209, v97, v85 row_shr:2 row_mask:0xf bank_mask:0xf
	v_fmac_f32_dpp v210, v98, v86 row_shr:2 row_mask:0xf bank_mask:0xf
	v_fmac_f32_dpp v211, v99, v87 row_shr:2 row_mask:0xf bank_mask:0xf
	v_fmac_f32_dpp v212, v92, v104 row_shr:2 row_mask:0xf bank_mask:0xf
	v_fmac_f32_dpp v213, v93, v105 row_shr:2 row_mask:0xf bank_mask:0xf
	v_fmac_f32_dpp v214, v94, v106 row_shr:2 row_mask:0xf bank_mask:0xf
	v_fmac_f32_dpp v215, v95, v107 row_shr:2 row_mask:0xf bank_mask:0xf
	v_fmac_f32_dpp v208, v112, v84 row_shl:14 row_mask:0xf bank_mask:0xf
	v_fmac_f32_dpp v209, v113, v85 row_shl:14 row_mask:0xf bank_mask:0xf
	v_fmac_f32_dpp v210, v114, v86 row_shl:14 row_mask:0xf bank_mask:0xf
	v_fmac_f32_dpp v211, v115, v87 row_shl:14 row_mask:0xf bank_mask:0xf
	v_fmac_f32_dpp v212, v108, v104 row_shl:14 row_mask:0xf bank_mask:0xf
	v_fmac_f32_dpp v213, v109, v105 row_shl:14 row_mask:0xf bank_mask:0xf
	v_fmac_f32_dpp v214, v110, v106 row_shl:14 row_mask:0xf bank_mask:0xf
	v_fmac_f32_dpp v215, v111, v107 row_shl:14 row_mask:0xf bank_mask:0xf
	v_mul_f32_e32 v216, 0xbfb8aa3b, v208
	v_mul_f32_e32 v217, 0xbfb8aa3b, v209
	v_mul_f32_e32 v218, 0xbfb8aa3b, v210
	v_mul_f32_e32 v219, 0xbfb8aa3b, v211
	v_exp_f32_e32 v216, v216
	v_exp_f32_e32 v217, v217
	v_exp_f32_e32 v218, v218
	v_exp_f32_e32 v219, v219
	v_add_f32_e32 v216, 1.0, v216
	v_add_f32_e32 v217, 1.0, v217
	v_add_f32_e32 v218, 1.0, v218
	v_add_f32_e32 v219, 1.0, v219
; DI float silu_fast(float x) { return x * __builtin_amdgcn_rcpf(1.f + __expf(-x)); }
; template <int CTRL> DI float dppf(float v) { return __builtin_bit_cast(float, __builtin_amdgcn_update_dpp(0, __builtin_bit_cast(int, v), CTRL, 0xf, 0xf, true)); }
; DI void Epi::fused(const f32x4 (&acc)[2][2][4][2], int pm, int pn, int wr, int wc, int fr, int fq) const {
;     ...
;             for (int m = 0; m < 4; ++m) {
;                 const f32x4 ca = acc[ai][bj][m][0], cb = acc[ai][bj][m][1];
;                 const int row = pm * 256 + ai * 128 + wr * 64 + m * 16 + fr;
;                 float o[4];
; #pragma unroll
;                 for (int e = 0; e < 4; ++e) {
;                     const float a1 = dppf<0x111>(ca[e]) + dppf<0x10F>(pa[e]), a2 = dppf<0x112>(ca[e]) + dppf<0x10E>(pa[e]);
;                     const float b1 = dppf<0x111>(cb[e]) + dppf<0x10F>(pb[e]), b2 = dppf<0x112>(cb[e]) + dppf<0x10E>(pb[e]);
;                     const float ya = fmaf(wa0[e], a2, fmaf(wa1[e], a1, fmaf(wa2[e], ca[e], ba[e])));
;                     const float yb = fmaf(wb0[e], b2, fmaf(wb1[e], b1, fmaf(wb2[e], cb[e], bb[e])));
;                     o[e] = silu_fast(ya) * yb; }
;                 if (m > 0 || fr >= 2) { u32x2 w; w.x = pk2(o[0], o[1]); w.y = pk2(o[2], o[3]); *(u32x2*)(E.d0 + (size_t)row * FFH + j0) = w; }
;                 if ((m == 0 && fr < 2) || (m == 3 && fr >= 14)) { float* hb = E.f0 + ((size_t)(row >> 6) * 4 + (m == 0 ? fr : fr - 12)) * FF2 + ncol; *(f32x4*)hb = ca; *(f32x4*)(hb + 4) = cb; }
;                 pa = ca; pb = cb;
	v_rcp_f32_e32 v216, v216
	v_rcp_f32_e32 v217, v217
	v_rcp_f32_e32 v218, v218
	v_rcp_f32_e32 v219, v219
	s_mov_b32 s80, 0x16000
	s_mov_b32 s81, 0
	v_lshl_add_u64 v[222:223], v[224:225], 0, s[80:81]
	v_mul_f32_e32 v208, v208, v216
	v_mul_f32_e32 v209, v209, v217
	v_mul_f32_e32 v210, v210, v218
	v_mul_f32_e32 v211, v211, v219
	v_mul_f32_e32 v208, v212, v208
	v_mul_f32_e32 v209, v213, v209
	v_mul_f32_e32 v210, v214, v210
	v_mul_f32_e32 v211, v215, v211
	v_cvt_pk_bf16_f32 v220, v208, v209
	v_cvt_pk_bf16_f32 v221, v210, v211
	global_store_dwordx2 v[222:223], v[220:221], off
	v_fma_f32 v160, v100, v80, v124
	v_fma_f32 v161, v101, v81, v125
	v_fma_f32 v162, v102, v82, v126
	v_fma_f32 v163, v103, v83, v127
	v_fma_f32 v164, v120, v76, v72
	v_fma_f32 v165, v121, v77, v73
	v_fma_f32 v166, v122, v78, v74
	v_fma_f32 v167, v123, v79, v75
	v_fmac_f32_dpp v160, v80, v88 row_shr:1 row_mask:0xf bank_mask:0xf
	v_fmac_f32_dpp v161, v81, v89 row_shr:1 row_mask:0xf bank_mask:0xf
	v_fmac_f32_dpp v162, v82, v90 row_shr:1 row_mask:0xf bank_mask:0xf
	v_fmac_f32_dpp v163, v83, v91 row_shr:1 row_mask:0xf bank_mask:0xf
	v_fmac_f32_dpp v164, v76, v116 row_shr:1 row_mask:0xf bank_mask:0xf
	v_fmac_f32_dpp v165, v77, v117 row_shr:1 row_mask:0xf bank_mask:0xf
	v_fmac_f32_dpp v166, v78, v118 row_shr:1 row_mask:0xf bank_mask:0xf
	v_fmac_f32_dpp v167, v79, v119 row_shr:1 row_mask:0xf bank_mask:0xf
	v_fmac_f32_dpp v160, v96, v88 row_shl:15 row_mask:0xf bank_mask:0xf
	v_fmac_f32_dpp v161, v97, v89 row_shl:15 row_mask:0xf bank_mask:0xf
	v_fmac_f32_dpp v162, v98, v90 row_shl:15 row_mask:0xf bank_mask:0xf
	v_fmac_f32_dpp v163, v99, v91 row_shl:15 row_mask:0xf bank_mask:0xf
	v_fmac_f32_dpp v164, v92, v116 row_shl:15 row_mask:0xf bank_mask:0xf
	v_fmac_f32_dpp v165, v93, v117 row_shl:15 row_mask:0xf bank_mask:0xf
	v_fmac_f32_dpp v166, v94, v118 row_shl:15 row_mask:0xf bank_mask:0xf
	v_fmac_f32_dpp v167, v95, v119 row_shl:15 row_mask:0xf bank_mask:0xf
	v_fmac_f32_dpp v160, v80, v84 row_shr:2 row_mask:0xf bank_mask:0xf
	v_fmac_f32_dpp v161, v81, v85 row_shr:2 row_mask:0xf bank_mask:0xf
	v_fmac_f32_dpp v162, v82, v86 row_shr:2 row_mask:0xf bank_mask:0xf
	v_fmac_f32_dpp v163, v83, v87 row_shr:2 row_mask:0xf bank_mask:0xf
	v_fmac_f32_dpp v164, v76, v104 row_shr:2 row_mask:0xf bank_mask:0xf
	v_fmac_f32_dpp v165, v77, v105 row_shr:2 row_mask:0xf bank_mask:0xf
	v_fmac_f32_dpp v166, v78, v106 row_shr:2 row_mask:0xf bank_mask:0xf
	v_fmac_f32_dpp v167, v79, v107 row_shr:2 row_mask:0xf bank_mask:0xf
	v_fmac_f32_dpp v160, v96, v84 row_shl:14 row_mask:0xf bank_mask:0xf
	v_fmac_f32_dpp v161, v97, v85 row_shl:14 row_mask:0xf bank_mask:0xf
	v_fmac_f32_dpp v162, v98, v86 row_shl:14 row_mask:0xf bank_mask:0xf
	v_fmac_f32_dpp v163, v99, v87 row_shl:14 row_mask:0xf bank_mask:0xf
	v_fmac_f32_dpp v164, v92, v104 row_shl:14 row_mask:0xf bank_mask:0xf
	v_fmac_f32_dpp v165, v93, v105 row_shl:14 row_mask:0xf bank_mask:0xf
	v_fmac_f32_dpp v166, v94, v106 row_shl:14 row_mask:0xf bank_mask:0xf
	v_fmac_f32_dpp v167, v95, v107 row_shl:14 row_mask:0xf bank_mask:0xf
	v_mul_f32_e32 v168, 0xbfb8aa3b, v160
	v_mul_f32_e32 v169, 0xbfb8aa3b, v161
	v_mul_f32_e32 v170, 0xbfb8aa3b, v162
	v_mul_f32_e32 v171, 0xbfb8aa3b, v163
	v_exp_f32_e32 v168, v168
	v_exp_f32_e32 v169, v169
	v_exp_f32_e32 v170, v170
	v_exp_f32_e32 v171, v171
	v_add_f32_e32 v168, 1.0, v168
	v_add_f32_e32 v169, 1.0, v169
	v_add_f32_e32 v170, 1.0, v170
	v_add_f32_e32 v171, 1.0, v171
	v_rcp_f32_e32 v168, v168
	v_rcp_f32_e32 v169, v169
	v_rcp_f32_e32 v170, v170
	v_rcp_f32_e32 v171, v171
	s_mov_b32 s80, 0x2c000
	s_mov_b32 s81, 0
	v_lshl_add_u64 v[174:175], v[224:225], 0, s[80:81]
	v_mul_f32_e32 v160, v160, v168
	v_mul_f32_e32 v161, v161, v169
	v_mul_f32_e32 v162, v162, v170
	v_mul_f32_e32 v163, v163, v171
	v_mul_f32_e32 v160, v164, v160
	v_mul_f32_e32 v161, v165, v161
	v_mul_f32_e32 v162, v166, v162
	v_mul_f32_e32 v163, v167, v163
	v_cvt_pk_bf16_f32 v172, v160, v161
	v_cvt_pk_bf16_f32 v173, v162, v163
	global_store_dwordx2 v[174:175], v[172:173], off
	v_fma_f32 v208, v100, v68, v124
	v_fma_f32 v209, v101, v69, v125
	v_fma_f32 v210, v102, v70, v126
	v_fma_f32 v211, v103, v71, v127
	v_fma_f32 v212, v120, v64, v72
	v_fma_f32 v213, v121, v65, v73
	v_fma_f32 v214, v122, v66, v74
	v_fma_f32 v215, v123, v67, v75
	v_fmac_f32_dpp v208, v68, v88 row_shr:1 row_mask:0xf bank_mask:0xf
	v_fmac_f32_dpp v209, v69, v89 row_shr:1 row_mask:0xf bank_mask:0xf
	v_fmac_f32_dpp v210, v70, v90 row_shr:1 row_mask:0xf bank_mask:0xf
	v_fmac_f32_dpp v211, v71, v91 row_shr:1 row_mask:0xf bank_mask:0xf
	v_fmac_f32_dpp v212, v64, v116 row_shr:1 row_mask:0xf bank_mask:0xf
	v_fmac_f32_dpp v213, v65, v117 row_shr:1 row_mask:0xf bank_mask:0xf
	v_fmac_f32_dpp v214, v66, v118 row_shr:1 row_mask:0xf bank_mask:0xf
	v_fmac_f32_dpp v215, v67, v119 row_shr:1 row_mask:0xf bank_mask:0xf
	v_fmac_f32_dpp v208, v80, v88 row_shl:15 row_mask:0xf bank_mask:0xf
	v_fmac_f32_dpp v209, v81, v89 row_shl:15 row_mask:0xf bank_mask:0xf
	v_fmac_f32_dpp v210, v82, v90 row_shl:15 row_mask:0xf bank_mask:0xf
	v_fmac_f32_dpp v211, v83, v91 row_shl:15 row_mask:0xf bank_mask:0xf
	v_fmac_f32_dpp v212, v76, v116 row_shl:15 row_mask:0xf bank_mask:0xf
	v_fmac_f32_dpp v213, v77, v117 row_shl:15 row_mask:0xf bank_mask:0xf
	v_fmac_f32_dpp v214, v78, v118 row_shl:15 row_mask:0xf bank_mask:0xf
	v_fmac_f32_dpp v215, v79, v119 row_shl:15 row_mask:0xf bank_mask:0xf
	v_fmac_f32_dpp v208, v68, v84 row_shr:2 row_mask:0xf bank_mask:0xf
	v_fmac_f32_dpp v209, v69, v85 row_shr:2 row_mask:0xf bank_mask:0xf
	v_fmac_f32_dpp v210, v70, v86 row_shr:2 row_mask:0xf bank_mask:0xf
	v_fmac_f32_dpp v211, v71, v87 row_shr:2 row_mask:0xf bank_mask:0xf
; DI float silu_fast(float x) { return x * __builtin_amdgcn_rcpf(1.f + __expf(-x)); }
; template <int CTRL> DI float dppf(float v) { return __builtin_bit_cast(float, __builtin_amdgcn_update_dpp(0, __builtin_bit_cast(int, v), CTRL, 0xf, 0xf, true)); }
; DI void Epi::fused(const f32x4 (&acc)[2][2][4][2], int pm, int pn, int wr, int wc, int fr, int fq) const {
;     ...
;             for (int m = 0; m < 4; ++m) {
;                 const f32x4 ca = acc[ai][bj][m][0], cb = acc[ai][bj][m][1];
;                 const int row = pm * 256 + ai * 128 + wr * 64 + m * 16 + fr;
;                 float o[4];
; #pragma unroll
;                 for (int e = 0; e < 4; ++e) {
;                     const float a1 = dppf<0x111>(ca[e]) + dppf<0x10F>(pa[e]), a2 = dppf<0x112>(ca[e]) + dppf<0x10E>(pa[e]);
;                     const float b1 = dppf<0x111>(cb[e]) + dppf<0x10F>(pb[e]), b2 = dppf<0x112>(cb[e]) + dppf<0x10E>(pb[e]);
;                     const float ya = fmaf(wa0[e], a2, fmaf(wa1[e], a1, fmaf(wa2[e], ca[e], ba[e])));
;                     const float yb = fmaf(wb0[e], b2, fmaf(wb1[e], b1, fmaf(wb2[e], cb[e], bb[e])));
;                     o[e] = silu_fast(ya) * yb; }
;                 if (m > 0 || fr >= 2) { u32x2 w; w.x = pk2(o[0], o[1]); w.y = pk2(o[2], o[3]); *(u32x2*)(E.d0 + (size_t)row * FFH + j0) = w; }
;                 if ((m == 0 && fr < 2) || (m == 3 && fr >= 14)) { float* hb = E.f0 + ((size_t)(row >> 6) * 4 + (m == 0 ? fr : fr - 12)) * FF2 + ncol; *(f32x4*)hb = ca; *(f32x4*)(hb + 4) = cb; }
;                 pa = ca; pb = cb;
	v_fmac_f32_dpp v212, v64, v104 row_shr:2 row_mask:0xf bank_mask:0xf
	v_fmac_f32_dpp v213, v65, v105 row_shr:2 row_mask:0xf bank_mask:0xf
	v_fmac_f32_dpp v214, v66, v106 row_shr:2 row_mask:0xf bank_mask:0xf
	v_fmac_f32_dpp v215, v67, v107 row_shr:2 row_mask:0xf bank_mask:0xf
	v_fmac_f32_dpp v208, v80, v84 row_shl:14 row_mask:0xf bank_mask:0xf
	v_fmac_f32_dpp v209, v81, v85 row_shl:14 row_mask:0xf bank_mask:0xf
	v_fmac_f32_dpp v210, v82, v86 row_shl:14 row_mask:0xf bank_mask:0xf
	v_fmac_f32_dpp v211, v83, v87 row_shl:14 row_mask:0xf bank_mask:0xf
	v_fmac_f32_dpp v212, v76, v104 row_shl:14 row_mask:0xf bank_mask:0xf
	v_fmac_f32_dpp v213, v77, v105 row_shl:14 row_mask:0xf bank_mask:0xf
	v_fmac_f32_dpp v214, v78, v106 row_shl:14 row_mask:0xf bank_mask:0xf
	v_fmac_f32_dpp v215, v79, v107 row_shl:14 row_mask:0xf bank_mask:0xf
	v_mul_f32_e32 v216, 0xbfb8aa3b, v208
	v_mul_f32_e32 v217, 0xbfb8aa3b, v209
	v_mul_f32_e32 v218, 0xbfb8aa3b, v210
	v_mul_f32_e32 v219, 0xbfb8aa3b, v211
	v_exp_f32_e32 v216, v216
	v_exp_f32_e32 v217, v217
	v_exp_f32_e32 v218, v218
	v_exp_f32_e32 v219, v219
	v_add_f32_e32 v216, 1.0, v216
	v_add_f32_e32 v217, 1.0, v217
	v_add_f32_e32 v218, 1.0, v218
	v_add_f32_e32 v219, 1.0, v219
	v_rcp_f32_e32 v216, v216
	v_rcp_f32_e32 v217, v217
	v_rcp_f32_e32 v218, v218
	v_rcp_f32_e32 v219, v219
	s_mov_b32 s80, 0x42000
	s_mov_b32 s81, 0
	v_lshl_add_u64 v[222:223], v[224:225], 0, s[80:81]
	v_mul_f32_e32 v208, v208, v216
	v_mul_f32_e32 v209, v209, v217
	v_mul_f32_e32 v210, v210, v218
	v_mul_f32_e32 v211, v211, v219
	v_mul_f32_e32 v208, v212, v208
	v_mul_f32_e32 v209, v213, v209
	v_mul_f32_e32 v210, v214, v210
	v_mul_f32_e32 v211, v215, v211
	v_cvt_pk_bf16_f32 v220, v208, v209
	v_cvt_pk_bf16_f32 v221, v210, v211
	global_store_dwordx2 v[222:223], v[220:221], off
	s_ashr_i32 s80, s71, 6
	s_lshl_b32 s80, s80, 2
	v_add_u32_e32 v226, s80, v190
	v_mov_b64_e32 v[222:223], s[8:9]
	s_movk_i32 s80, 0x5800
	v_mad_i64_i32 v[222:223], s[78:79], v226, s80, v[222:223]
	v_lshl_add_u64 v[222:223], v[228:229], 2, v[222:223]
	s_and_saveexec_b64 s[76:77], s[42:43]
	global_store_dwordx4 v[222:223], v[68:71], off
	global_store_dwordx4 v[222:223], v[64:67], off offset:16
	s_or_b64 exec, exec, s[76:77]
	v_add_u32_e32 v228, 128, v199
	v_mov_b64_e32 v[224:225], s[12:13]
	s_movk_i32 s80, 0x1600
	v_mad_i64_i32 v[224:225], s[78:79], v228, s80, v[224:225]
	v_add_u32_e32 v228, 128, v240
	v_mov_b32_e32 v229, 0
	v_lshl_add_u64 v[224:225], v[228:229], 0, v[224:225]
	v_fma_f32 v160, v100, v48, v124
	v_fma_f32 v161, v101, v49, v125
	v_fma_f32 v162, v102, v50, v126
	v_fma_f32 v163, v103, v51, v127
	v_fma_f32 v164, v120, v44, v72
	v_fma_f32 v165, v121, v45, v73
	v_fma_f32 v166, v122, v46, v74
	v_fma_f32 v167, v123, v47, v75
	v_fmac_f32_dpp v160, v48, v88 row_shr:1 row_mask:0xf bank_mask:0xf
	v_fmac_f32_dpp v161, v49, v89 row_shr:1 row_mask:0xf bank_mask:0xf
	v_fmac_f32_dpp v162, v50, v90 row_shr:1 row_mask:0xf bank_mask:0xf
	v_fmac_f32_dpp v163, v51, v91 row_shr:1 row_mask:0xf bank_mask:0xf
	v_fmac_f32_dpp v164, v44, v116 row_shr:1 row_mask:0xf bank_mask:0xf
	v_fmac_f32_dpp v165, v45, v117 row_shr:1 row_mask:0xf bank_mask:0xf
	v_fmac_f32_dpp v166, v46, v118 row_shr:1 row_mask:0xf bank_mask:0xf
	v_fmac_f32_dpp v167, v47, v119 row_shr:1 row_mask:0xf bank_mask:0xf
	v_fmac_f32_dpp v160, v48, v84 row_shr:2 row_mask:0xf bank_mask:0xf
	v_fmac_f32_dpp v161, v49, v85 row_shr:2 row_mask:0xf bank_mask:0xf
	v_fmac_f32_dpp v162, v50, v86 row_shr:2 row_mask:0xf bank_mask:0xf
	v_fmac_f32_dpp v163, v51, v87 row_shr:2 row_mask:0xf bank_mask:0xf
	v_fmac_f32_dpp v164, v44, v104 row_shr:2 row_mask:0xf bank_mask:0xf
	v_fmac_f32_dpp v165, v45, v105 row_shr:2 row_mask:0xf bank_mask:0xf
	v_fmac_f32_dpp v166, v46, v106 row_shr:2 row_mask:0xf bank_mask:0xf
	v_fmac_f32_dpp v167, v47, v107 row_shr:2 row_mask:0xf bank_mask:0xf
	v_mul_f32_e32 v168, 0xbfb8aa3b, v160
	v_mul_f32_e32 v169, 0xbfb8aa3b, v161
	v_mul_f32_e32 v170, 0xbfb8aa3b, v162
	v_mul_f32_e32 v171, 0xbfb8aa3b, v163
	v_exp_f32_e32 v168, v168
	v_exp_f32_e32 v169, v169
	v_exp_f32_e32 v170, v170
	v_exp_f32_e32 v171, v171
	v_add_f32_e32 v168, 1.0, v168
	v_add_f32_e32 v169, 1.0, v169
	v_add_f32_e32 v170, 1.0, v170
	v_add_f32_e32 v171, 1.0, v171
	v_rcp_f32_e32 v168, v168
	v_rcp_f32_e32 v169, v169
	v_rcp_f32_e32 v170, v170
	v_rcp_f32_e32 v171, v171
	v_mov_b64_e32 v[174:175], v[224:225]
	v_mul_f32_e32 v160, v160, v168
	v_mul_f32_e32 v161, v161, v169
	v_mul_f32_e32 v162, v162, v170
	v_mul_f32_e32 v163, v163, v171
	v_mul_f32_e32 v160, v164, v160
	v_mul_f32_e32 v161, v165, v161
	v_mul_f32_e32 v162, v166, v162
	v_mul_f32_e32 v163, v167, v163
	v_cvt_pk_bf16_f32 v172, v160, v161
	v_cvt_pk_bf16_f32 v173, v162, v163
	s_and_saveexec_b64 s[76:77], s[38:39]
	global_store_dwordx2 v[174:175], v[172:173], off
	s_or_b64 exec, exec, s[76:77]
	s_ashr_i32 s80, s71, 6
	s_lshl_b32 s80, s80, 2
	s_add_i32 s80, s80, 8
	v_add_u32_e32 v226, s80, v188
	v_mov_b64_e32 v[174:175], s[8:9]
	s_movk_i32 s80, 0x5800
	v_mad_i64_i32 v[174:175], s[78:79], v226, s80, v[174:175]
	v_lshl_add_u64 v[174:175], v[228:229], 2, v[174:175]
	s_and_saveexec_b64 s[76:77], s[40:41]
	global_store_dwordx4 v[174:175], v[48:51], off
	global_store_dwordx4 v[174:175], v[44:47], off offset:16
	s_or_b64 exec, exec, s[76:77]
	v_fma_f32 v208, v100, v24, v124
	v_fma_f32 v209, v101, v25, v125
	v_fma_f32 v210, v102, v26, v126
	v_fma_f32 v211, v103, v27, v127
	v_fma_f32 v212, v120, v20, v72
	v_fma_f32 v213, v121, v21, v73
	v_fma_f32 v214, v122, v22, v74
	v_fma_f32 v215, v123, v23, v75
	v_fmac_f32_dpp v208, v24, v88 row_shr:1 row_mask:0xf bank_mask:0xf
	v_fmac_f32_dpp v209, v25, v89 row_shr:1 row_mask:0xf bank_mask:0xf
; DI float silu_fast(float x) { return x * __builtin_amdgcn_rcpf(1.f + __expf(-x)); }
; template <int CTRL> DI float dppf(float v) { return __builtin_bit_cast(float, __builtin_amdgcn_update_dpp(0, __builtin_bit_cast(int, v), CTRL, 0xf, 0xf, true)); }
; DI void Epi::fused(const f32x4 (&acc)[2][2][4][2], int pm, int pn, int wr, int wc, int fr, int fq) const {
;     ...
;             for (int m = 0; m < 4; ++m) {
;                 const f32x4 ca = acc[ai][bj][m][0], cb = acc[ai][bj][m][1];
;                 const int row = pm * 256 + ai * 128 + wr * 64 + m * 16 + fr;
;                 float o[4];
; #pragma unroll
;                 for (int e = 0; e < 4; ++e) {
;                     const float a1 = dppf<0x111>(ca[e]) + dppf<0x10F>(pa[e]), a2 = dppf<0x112>(ca[e]) + dppf<0x10E>(pa[e]);
;                     const float b1 = dppf<0x111>(cb[e]) + dppf<0x10F>(pb[e]), b2 = dppf<0x112>(cb[e]) + dppf<0x10E>(pb[e]);
;                     const float ya = fmaf(wa0[e], a2, fmaf(wa1[e], a1, fmaf(wa2[e], ca[e], ba[e])));
;                     const float yb = fmaf(wb0[e], b2, fmaf(wb1[e], b1, fmaf(wb2[e], cb[e], bb[e])));
;                     o[e] = silu_fast(ya) * yb; }
;                 if (m > 0 || fr >= 2) { u32x2 w; w.x = pk2(o[0], o[1]); w.y = pk2(o[2], o[3]); *(u32x2*)(E.d0 + (size_t)row * FFH + j0) = w; }
;                 if ((m == 0 && fr < 2) || (m == 3 && fr >= 14)) { float* hb = E.f0 + ((size_t)(row >> 6) * 4 + (m == 0 ? fr : fr - 12)) * FF2 + ncol; *(f32x4*)hb = ca; *(f32x4*)(hb + 4) = cb; }
;                 pa = ca; pb = cb;
	v_fmac_f32_dpp v210, v26, v90 row_shr:1 row_mask:0xf bank_mask:0xf
	v_fmac_f32_dpp v211, v27, v91 row_shr:1 row_mask:0xf bank_mask:0xf
	v_fmac_f32_dpp v212, v20, v116 row_shr:1 row_mask:0xf bank_mask:0xf
	v_fmac_f32_dpp v213, v21, v117 row_shr:1 row_mask:0xf bank_mask:0xf
	v_fmac_f32_dpp v214, v22, v118 row_shr:1 row_mask:0xf bank_mask:0xf
	v_fmac_f32_dpp v215, v23, v119 row_shr:1 row_mask:0xf bank_mask:0xf
	v_fmac_f32_dpp v208, v48, v88 row_shl:15 row_mask:0xf bank_mask:0xf
	v_fmac_f32_dpp v209, v49, v89 row_shl:15 row_mask:0xf bank_mask:0xf
	v_fmac_f32_dpp v210, v50, v90 row_shl:15 row_mask:0xf bank_mask:0xf
	v_fmac_f32_dpp v211, v51, v91 row_shl:15 row_mask:0xf bank_mask:0xf
	v_fmac_f32_dpp v212, v44, v116 row_shl:15 row_mask:0xf bank_mask:0xf
	v_fmac_f32_dpp v213, v45, v117 row_shl:15 row_mask:0xf bank_mask:0xf
	v_fmac_f32_dpp v214, v46, v118 row_shl:15 row_mask:0xf bank_mask:0xf
	v_fmac_f32_dpp v215, v47, v119 row_shl:15 row_mask:0xf bank_mask:0xf
	v_fmac_f32_dpp v208, v24, v84 row_shr:2 row_mask:0xf bank_mask:0xf
	v_fmac_f32_dpp v209, v25, v85 row_shr:2 row_mask:0xf bank_mask:0xf
	v_fmac_f32_dpp v210, v26, v86 row_shr:2 row_mask:0xf bank_mask:0xf
	v_fmac_f32_dpp v211, v27, v87 row_shr:2 row_mask:0xf bank_mask:0xf
	v_fmac_f32_dpp v212, v20, v104 row_shr:2 row_mask:0xf bank_mask:0xf
	v_fmac_f32_dpp v213, v21, v105 row_shr:2 row_mask:0xf bank_mask:0xf
	v_fmac_f32_dpp v214, v22, v106 row_shr:2 row_mask:0xf bank_mask:0xf
	v_fmac_f32_dpp v215, v23, v107 row_shr:2 row_mask:0xf bank_mask:0xf
	v_fmac_f32_dpp v208, v48, v84 row_shl:14 row_mask:0xf bank_mask:0xf
	v_fmac_f32_dpp v209, v49, v85 row_shl:14 row_mask:0xf bank_mask:0xf
	v_fmac_f32_dpp v210, v50, v86 row_shl:14 row_mask:0xf bank_mask:0xf
	v_fmac_f32_dpp v211, v51, v87 row_shl:14 row_mask:0xf bank_mask:0xf
	v_fmac_f32_dpp v212, v44, v104 row_shl:14 row_mask:0xf bank_mask:0xf
	v_fmac_f32_dpp v213, v45, v105 row_shl:14 row_mask:0xf bank_mask:0xf
	v_fmac_f32_dpp v214, v46, v106 row_shl:14 row_mask:0xf bank_mask:0xf
	v_fmac_f32_dpp v215, v47, v107 row_shl:14 row_mask:0xf bank_mask:0xf
	v_mul_f32_e32 v216, 0xbfb8aa3b, v208
	v_mul_f32_e32 v217, 0xbfb8aa3b, v209
	v_mul_f32_e32 v218, 0xbfb8aa3b, v210
	v_mul_f32_e32 v219, 0xbfb8aa3b, v211
	v_exp_f32_e32 v216, v216
	v_exp_f32_e32 v217, v217
	v_exp_f32_e32 v218, v218
	v_exp_f32_e32 v219, v219
	v_add_f32_e32 v216, 1.0, v216
	v_add_f32_e32 v217, 1.0, v217
	v_add_f32_e32 v218, 1.0, v218
	v_add_f32_e32 v219, 1.0, v219
	v_rcp_f32_e32 v216, v216
	v_rcp_f32_e32 v217, v217
	v_rcp_f32_e32 v218, v218
	v_rcp_f32_e32 v219, v219
	s_mov_b32 s80, 0x16000
	s_mov_b32 s81, 0
	v_lshl_add_u64 v[222:223], v[224:225], 0, s[80:81]
	v_mul_f32_e32 v208, v208, v216
	v_mul_f32_e32 v209, v209, v217
	v_mul_f32_e32 v210, v210, v218
	v_mul_f32_e32 v211, v211, v219
	v_mul_f32_e32 v208, v212, v208
	v_mul_f32_e32 v209, v213, v209
	v_mul_f32_e32 v210, v214, v210
	v_mul_f32_e32 v211, v215, v211
	v_cvt_pk_bf16_f32 v220, v208, v209
	v_cvt_pk_bf16_f32 v221, v210, v211
	global_store_dwordx2 v[222:223], v[220:221], off
	v_fma_f32 v160, v100, v28, v124
	v_fma_f32 v161, v101, v29, v125
	v_fma_f32 v162, v102, v30, v126
	v_fma_f32 v163, v103, v31, v127
	v_fma_f32 v164, v120, v32, v72
	v_fma_f32 v165, v121, v33, v73
	v_fma_f32 v166, v122, v34, v74
	v_fma_f32 v167, v123, v35, v75
	v_fmac_f32_dpp v160, v28, v88 row_shr:1 row_mask:0xf bank_mask:0xf
	v_fmac_f32_dpp v161, v29, v89 row_shr:1 row_mask:0xf bank_mask:0xf
	v_fmac_f32_dpp v162, v30, v90 row_shr:1 row_mask:0xf bank_mask:0xf
	v_fmac_f32_dpp v163, v31, v91 row_shr:1 row_mask:0xf bank_mask:0xf
	v_fmac_f32_dpp v164, v32, v116 row_shr:1 row_mask:0xf bank_mask:0xf
	v_fmac_f32_dpp v165, v33, v117 row_shr:1 row_mask:0xf bank_mask:0xf
	v_fmac_f32_dpp v166, v34, v118 row_shr:1 row_mask:0xf bank_mask:0xf
	v_fmac_f32_dpp v167, v35, v119 row_shr:1 row_mask:0xf bank_mask:0xf
	v_fmac_f32_dpp v160, v24, v88 row_shl:15 row_mask:0xf bank_mask:0xf
	v_fmac_f32_dpp v161, v25, v89 row_shl:15 row_mask:0xf bank_mask:0xf
	v_fmac_f32_dpp v162, v26, v90 row_shl:15 row_mask:0xf bank_mask:0xf
	v_fmac_f32_dpp v163, v27, v91 row_shl:15 row_mask:0xf bank_mask:0xf
	v_fmac_f32_dpp v164, v20, v116 row_shl:15 row_mask:0xf bank_mask:0xf
	v_fmac_f32_dpp v165, v21, v117 row_shl:15 row_mask:0xf bank_mask:0xf
	v_fmac_f32_dpp v166, v22, v118 row_shl:15 row_mask:0xf bank_mask:0xf
	v_fmac_f32_dpp v167, v23, v119 row_shl:15 row_mask:0xf bank_mask:0xf
	v_fmac_f32_dpp v160, v28, v84 row_shr:2 row_mask:0xf bank_mask:0xf
	v_fmac_f32_dpp v161, v29, v85 row_shr:2 row_mask:0xf bank_mask:0xf
	v_fmac_f32_dpp v162, v30, v86 row_shr:2 row_mask:0xf bank_mask:0xf
	v_fmac_f32_dpp v163, v31, v87 row_shr:2 row_mask:0xf bank_mask:0xf
	v_fmac_f32_dpp v164, v32, v104 row_shr:2 row_mask:0xf bank_mask:0xf
	v_fmac_f32_dpp v165, v33, v105 row_shr:2 row_mask:0xf bank_mask:0xf
	v_fmac_f32_dpp v166, v34, v106 row_shr:2 row_mask:0xf bank_mask:0xf
	v_fmac_f32_dpp v167, v35, v107 row_shr:2 row_mask:0xf bank_mask:0xf
	v_fmac_f32_dpp v160, v24, v84 row_shl:14 row_mask:0xf bank_mask:0xf
	v_fmac_f32_dpp v161, v25, v85 row_shl:14 row_mask:0xf bank_mask:0xf
	v_fmac_f32_dpp v162, v26, v86 row_shl:14 row_mask:0xf bank_mask:0xf
; DI float silu_fast(float x) { return x * __builtin_amdgcn_rcpf(1.f + __expf(-x)); }
; template <int CTRL> DI float dppf(float v) { return __builtin_bit_cast(float, __builtin_amdgcn_update_dpp(0, __builtin_bit_cast(int, v), CTRL, 0xf, 0xf, true)); }
; DI void Epi::fused(const f32x4 (&acc)[2][2][4][2], int pm, int pn, int wr, int wc, int fr, int fq) const {
;     ...
;             for (int m = 0; m < 4; ++m) {
;                 const f32x4 ca = acc[ai][bj][m][0], cb = acc[ai][bj][m][1];
;                 const int row = pm * 256 + ai * 128 + wr * 64 + m * 16 + fr;
;                 float o[4];
; #pragma unroll
;                 for (int e = 0; e < 4; ++e) {
;                     const float a1 = dppf<0x111>(ca[e]) + dppf<0x10F>(pa[e]), a2 = dppf<0x112>(ca[e]) + dppf<0x10E>(pa[e]);
;                     const float b1 = dppf<0x111>(cb[e]) + dppf<0x10F>(pb[e]), b2 = dppf<0x112>(cb[e]) + dppf<0x10E>(pb[e]);
;                     const float ya = fmaf(wa0[e], a2, fmaf(wa1[e], a1, fmaf(wa2[e], ca[e], ba[e])));
;                     const float yb = fmaf(wb0[e], b2, fmaf(wb1[e], b1, fmaf(wb2[e], cb[e], bb[e])));
;                     o[e] = silu_fast(ya) * yb; }
;                 if (m > 0 || fr >= 2) { u32x2 w; w.x = pk2(o[0], o[1]); w.y = pk2(o[2], o[3]); *(u32x2*)(E.d0 + (size_t)row * FFH + j0) = w; }
;                 if ((m == 0 && fr < 2) || (m == 3 && fr >= 14)) { float* hb = E.f0 + ((size_t)(row >> 6) * 4 + (m == 0 ? fr : fr - 12)) * FF2 + ncol; *(f32x4*)hb = ca; *(f32x4*)(hb + 4) = cb; }
;                 pa = ca; pb = cb;
	v_fmac_f32_dpp v163, v27, v87 row_shl:14 row_mask:0xf bank_mask:0xf
	v_fmac_f32_dpp v164, v20, v104 row_shl:14 row_mask:0xf bank_mask:0xf
	v_fmac_f32_dpp v165, v21, v105 row_shl:14 row_mask:0xf bank_mask:0xf
	v_fmac_f32_dpp v166, v22, v106 row_shl:14 row_mask:0xf bank_mask:0xf
	v_fmac_f32_dpp v167, v23, v107 row_shl:14 row_mask:0xf bank_mask:0xf
	v_mul_f32_e32 v168, 0xbfb8aa3b, v160
	v_mul_f32_e32 v169, 0xbfb8aa3b, v161
	v_mul_f32_e32 v170, 0xbfb8aa3b, v162
	v_mul_f32_e32 v171, 0xbfb8aa3b, v163
	v_exp_f32_e32 v168, v168
	v_exp_f32_e32 v169, v169
	v_exp_f32_e32 v170, v170
	v_exp_f32_e32 v171, v171
	v_add_f32_e32 v168, 1.0, v168
	v_add_f32_e32 v169, 1.0, v169
	v_add_f32_e32 v170, 1.0, v170
	v_add_f32_e32 v171, 1.0, v171
	v_rcp_f32_e32 v168, v168
	v_rcp_f32_e32 v169, v169
	v_rcp_f32_e32 v170, v170
	v_rcp_f32_e32 v171, v171
	s_mov_b32 s80, 0x2c000
	s_mov_b32 s81, 0
	v_lshl_add_u64 v[174:175], v[224:225], 0, s[80:81]
	v_mul_f32_e32 v160, v160, v168
	v_mul_f32_e32 v161, v161, v169
	v_mul_f32_e32 v162, v162, v170
	v_mul_f32_e32 v163, v163, v171
	v_mul_f32_e32 v160, v164, v160
	v_mul_f32_e32 v161, v165, v161
	v_mul_f32_e32 v162, v166, v162
	v_mul_f32_e32 v163, v167, v163
	v_cvt_pk_bf16_f32 v172, v160, v161
	v_cvt_pk_bf16_f32 v173, v162, v163
	global_store_dwordx2 v[174:175], v[172:173], off
	v_fma_f32 v208, v100, v8, v124
	v_fma_f32 v209, v101, v9, v125
	v_fma_f32 v210, v102, v10, v126
	v_fma_f32 v211, v103, v11, v127
	v_fma_f32 v212, v120, v4, v72
	v_fma_f32 v213, v121, v5, v73
	v_fma_f32 v214, v122, v6, v74
	v_fma_f32 v215, v123, v7, v75
	v_fmac_f32_dpp v208, v8, v88 row_shr:1 row_mask:0xf bank_mask:0xf
	v_fmac_f32_dpp v209, v9, v89 row_shr:1 row_mask:0xf bank_mask:0xf
	v_fmac_f32_dpp v210, v10, v90 row_shr:1 row_mask:0xf bank_mask:0xf
	v_fmac_f32_dpp v211, v11, v91 row_shr:1 row_mask:0xf bank_mask:0xf
	v_fmac_f32_dpp v212, v4, v116 row_shr:1 row_mask:0xf bank_mask:0xf
	v_fmac_f32_dpp v213, v5, v117 row_shr:1 row_mask:0xf bank_mask:0xf
	v_fmac_f32_dpp v214, v6, v118 row_shr:1 row_mask:0xf bank_mask:0xf
	v_fmac_f32_dpp v215, v7, v119 row_shr:1 row_mask:0xf bank_mask:0xf
	v_fmac_f32_dpp v208, v28, v88 row_shl:15 row_mask:0xf bank_mask:0xf
	v_fmac_f32_dpp v209, v29, v89 row_shl:15 row_mask:0xf bank_mask:0xf
	v_fmac_f32_dpp v210, v30, v90 row_shl:15 row_mask:0xf bank_mask:0xf
	v_fmac_f32_dpp v211, v31, v91 row_shl:15 row_mask:0xf bank_mask:0xf
	v_fmac_f32_dpp v212, v32, v116 row_shl:15 row_mask:0xf bank_mask:0xf
	v_fmac_f32_dpp v213, v33, v117 row_shl:15 row_mask:0xf bank_mask:0xf
	v_fmac_f32_dpp v214, v34, v118 row_shl:15 row_mask:0xf bank_mask:0xf
	v_fmac_f32_dpp v215, v35, v119 row_shl:15 row_mask:0xf bank_mask:0xf
	v_fmac_f32_dpp v208, v8, v84 row_shr:2 row_mask:0xf bank_mask:0xf
	v_fmac_f32_dpp v209, v9, v85 row_shr:2 row_mask:0xf bank_mask:0xf
	v_fmac_f32_dpp v210, v10, v86 row_shr:2 row_mask:0xf bank_mask:0xf
	v_fmac_f32_dpp v211, v11, v87 row_shr:2 row_mask:0xf bank_mask:0xf
	v_fmac_f32_dpp v212, v4, v104 row_shr:2 row_mask:0xf bank_mask:0xf
	v_fmac_f32_dpp v213, v5, v105 row_shr:2 row_mask:0xf bank_mask:0xf
	v_fmac_f32_dpp v214, v6, v106 row_shr:2 row_mask:0xf bank_mask:0xf
	v_fmac_f32_dpp v215, v7, v107 row_shr:2 row_mask:0xf bank_mask:0xf
	v_fmac_f32_dpp v208, v28, v84 row_shl:14 row_mask:0xf bank_mask:0xf
	v_fmac_f32_dpp v209, v29, v85 row_shl:14 row_mask:0xf bank_mask:0xf
	v_fmac_f32_dpp v210, v30, v86 row_shl:14 row_mask:0xf bank_mask:0xf
	v_fmac_f32_dpp v211, v31, v87 row_shl:14 row_mask:0xf bank_mask:0xf
	v_fmac_f32_dpp v212, v32, v104 row_shl:14 row_mask:0xf bank_mask:0xf
	v_fmac_f32_dpp v213, v33, v105 row_shl:14 row_mask:0xf bank_mask:0xf
	v_fmac_f32_dpp v214, v34, v106 row_shl:14 row_mask:0xf bank_mask:0xf
	v_fmac_f32_dpp v215, v35, v107 row_shl:14 row_mask:0xf bank_mask:0xf
	v_mul_f32_e32 v216, 0xbfb8aa3b, v208
	v_mul_f32_e32 v217, 0xbfb8aa3b, v209
	v_mul_f32_e32 v218, 0xbfb8aa3b, v210
	v_mul_f32_e32 v219, 0xbfb8aa3b, v211
	v_exp_f32_e32 v216, v216
	v_exp_f32_e32 v217, v217
	v_exp_f32_e32 v218, v218
	v_exp_f32_e32 v219, v219
	v_add_f32_e32 v216, 1.0, v216
	v_add_f32_e32 v217, 1.0, v217
	v_add_f32_e32 v218, 1.0, v218
	v_add_f32_e32 v219, 1.0, v219
	v_rcp_f32_e32 v216, v216
	v_rcp_f32_e32 v217, v217
	v_rcp_f32_e32 v218, v218
	v_rcp_f32_e32 v219, v219
	s_mov_b32 s80, 0x42000
	s_mov_b32 s81, 0
	v_lshl_add_u64 v[222:223], v[224:225], 0, s[80:81]
	v_mul_f32_e32 v208, v208, v216
	v_mul_f32_e32 v209, v209, v217
	v_mul_f32_e32 v210, v210, v218
	v_mul_f32_e32 v211, v211, v219
	v_mul_f32_e32 v208, v212, v208
	v_mul_f32_e32 v209, v213, v209
	v_mul_f32_e32 v210, v214, v210
	v_mul_f32_e32 v211, v215, v211
	v_cvt_pk_bf16_f32 v220, v208, v209
	v_cvt_pk_bf16_f32 v221, v210, v211
	global_store_dwordx2 v[222:223], v[220:221], off
	s_ashr_i32 s80, s71, 6
	s_lshl_b32 s80, s80, 2
	s_add_i32 s80, s80, 8
	v_add_u32_e32 v226, s80, v190
	v_mov_b64_e32 v[222:223], s[8:9]
	s_movk_i32 s80, 0x5800
	v_mad_i64_i32 v[222:223], s[78:79], v226, s80, v[222:223]
	v_lshl_add_u64 v[222:223], v[228:229], 2, v[222:223]
	s_and_saveexec_b64 s[76:77], s[42:43]
	global_store_dwordx4 v[222:223], v[8:11], off
	global_store_dwordx4 v[222:223], v[4:7], off offset:16
	s_or_b64 exec, exec, s[76:77]
